# fused-RMSNorm rstd tables at the head of the FFN-up / w_in GEMM phases: all 8 blocks' global loads issued before a single vmcnt(0), reduce+rsqrt+LDS write afterwards (was 8 serial round trips)
# speedup vs baseline: 1.0053x; 1.0032x over previous
.LBB0_52:
	s_and_b64 vcc, exec, s[26:27]
	s_cbranch_vccz .LBB0_84
	s_mov_b64 s[28:29], s[0:1]
	s_mov_b64 s[30:31], s[0:1]
	s_mov_b64 s[38:39], s[0:1]
	s_mov_b64 s[10:11], s[0:1]
	s_load_dwordx2 s[10:11], s[10:11], 0xf8
	v_mov_b32_e32 v8, v186
	s_waitcnt lgkmcnt(0)
	v_mov_b64_e32 v[0:1], s[2:3]
	v_ashrrev_i32_e32 v3, 8, v8
	s_add_u32 s26, s10, 0x1e114000
	s_addc_u32 s27, s11, 0
	v_mad_i64_i32 v[0:1], s[10:11], v3, s56, v[0:1]
	v_and_b32_e32 v4, 0xff, v8
	v_readlane_b32 s6, v254, 59
	s_mov_b64 s[10:11], 0xb00
	v_readfirstlane_b32 s9, v8
	v_lshl_add_u32 v2, v4, 2, s6
	v_cmp_gt_i64_e32 vcc, s[10:11], v[0:1]
	v_lshlrev_b32_e32 v140, 6, v4
	s_and_saveexec_b64 s[34:35], vcc
	s_cbranch_execz .LBB0_55
	v_ashrrev_i32_e32 v1, 31, v0
	v_lshrrev_b32_e32 v1, 29, v1
	v_add_u32_e32 v1, v0, v1
	v_ashrrev_i32_e32 v4, 3, v1
	v_and_b32_e32 v1, -8, v1
	v_sub_u32_e32 v0, v0, v1
	v_cmp_gt_i32_e32 vcc, 0, v0
	v_mov_b32_e32 v1, 0x161
	v_mov_b32_e32 v5, 0x160
	v_cndmask_b32_e32 v1, v5, v1, vcc
	v_mad_u64_u32 v[0:1], s[10:11], v0, v1, v[4:5]
	s_mov_b32 s6, 0x2e8ba2e9
	v_mul_hi_i32 v1, v0, s6
	v_lshrrev_b32_e32 v4, 31, v1
	v_ashrrev_i32_e32 v1, 9, v1
	v_add_u32_e32 v1, v1, v4
	v_mul_i32_i24_e32 v1, 0xb00, v1
	v_sub_u32_e32 v0, v0, v1
	s_movk_i32 s6, 0xba3
	v_mul_i32_i24_sdwa v1, sext(v0), s6 dst_sel:DWORD dst_unused:UNUSED_PAD src0_sel:WORD_0 src1_sel:DWORD
	v_lshrrev_b32_e32 v4, 31, v1
	v_ashrrev_i32_e32 v1, 19, v1
	v_add_u16_e32 v1, v1, v4
	v_mul_lo_u16_e32 v4, 0xb0, v1
	v_sub_u16_e32 v0, v0, v4
	v_ashrrev_i16_e32 v4, 15, v0
	v_lshrrev_b16_e32 v4, 13, v4
	v_add_u16_e32 v4, v0, v4
	v_and_b32_e32 v4, -8, v4
	v_sub_u16_e32 v0, v0, v4
	v_bfe_i32 v1, v1, 0, 16
	v_bfe_i32 v0, v0, 0, 16
	v_lshl_add_u32 v0, v1, 3, v0
	v_ashrrev_i32_e32 v1, 31, v0
	v_lshlrev_b64 v[0:1], 14, v[0:1]
	v_lshl_add_u64 v[0:1], s[26:27], 0, v[0:1]
	v_lshl_add_u64 v[0:1], v[0:1], 0, v[140:141]
	global_load_dwordx4 v[32:35], v[0:1], off
	global_load_dwordx4 v[36:39], v[0:1], off offset:16
	global_load_dwordx4 v[40:43], v[0:1], off offset:32
	global_load_dwordx4 v[44:47], v[0:1], off offset:48
.LBB0_55:
	s_or_b64 exec, exec, s[34:35]
	s_load_dwordx2 s[34:35], s[28:29], 0xf8
	s_nop 0
	s_load_dwordx2 s[30:31], s[30:31], 0xf8
	s_nop 0
	s_load_dwordx2 s[28:29], s[38:39], 0xf8
	v_add_u32_e32 v4, 2, v3
	v_mov_b64_e32 v[0:1], s[2:3]
	v_mad_i64_i32 v[0:1], s[10:11], v4, s56, v[0:1]
	s_mov_b64 s[10:11], 0xb00
	s_nop 0
	v_cmp_gt_i64_e32 vcc, s[10:11], v[0:1]
	s_and_saveexec_b64 s[38:39], vcc
	s_cbranch_execz .LBB0_57
	v_ashrrev_i32_e32 v1, 31, v0
	v_lshrrev_b32_e32 v1, 29, v1
	v_add_u32_e32 v1, v0, v1
	v_ashrrev_i32_e32 v6, 3, v1
	v_and_b32_e32 v1, -8, v1
	v_sub_u32_e32 v0, v0, v1
	v_cmp_gt_i32_e32 vcc, 0, v0
	v_mov_b32_e32 v1, 0x161
	v_mov_b32_e32 v5, 0x160
	v_cndmask_b32_e32 v1, v5, v1, vcc
	v_mad_u64_u32 v[0:1], s[10:11], v0, v1, v[6:7]
	s_mov_b32 s6, 0x2e8ba2e9
	v_mul_hi_i32 v1, v0, s6
	v_lshrrev_b32_e32 v5, 31, v1
	v_ashrrev_i32_e32 v1, 9, v1
	v_add_u32_e32 v1, v1, v5
	v_mul_i32_i24_e32 v1, 0xb00, v1
	v_sub_u32_e32 v0, v0, v1
	s_movk_i32 s6, 0xba3
	v_mul_i32_i24_sdwa v1, sext(v0), s6 dst_sel:DWORD dst_unused:UNUSED_PAD src0_sel:WORD_0 src1_sel:DWORD
	v_lshrrev_b32_e32 v5, 31, v1
	v_ashrrev_i32_e32 v1, 19, v1
	v_add_u16_e32 v1, v1, v5
	v_mul_lo_u16_e32 v5, 0xb0, v1
	v_sub_u16_e32 v0, v0, v5
	v_ashrrev_i16_e32 v5, 15, v0
	v_lshrrev_b16_e32 v5, 13, v5
	v_add_u16_e32 v5, v0, v5
	v_and_b32_e32 v5, -8, v5
	v_sub_u16_e32 v0, v0, v5
	v_bfe_i32 v1, v1, 0, 16
	v_bfe_i32 v0, v0, 0, 16
	v_lshl_add_u32 v0, v1, 3, v0
	v_ashrrev_i32_e32 v1, 31, v0
	v_lshlrev_b64 v[0:1], 14, v[0:1]
	v_lshl_add_u64 v[0:1], s[26:27], 0, v[0:1]
	v_lshl_add_u64 v[0:1], v[0:1], 0, v[140:141]
	global_load_dwordx4 v[48:51], v[0:1], off
	global_load_dwordx4 v[52:55], v[0:1], off offset:16
	global_load_dwordx4 v[56:59], v[0:1], off offset:32
	global_load_dwordx4 v[60:63], v[0:1], off offset:48
.LBB0_57:
	s_or_b64 exec, exec, s[38:39]
	v_add_u32_e32 v4, 4, v3
	v_mov_b64_e32 v[0:1], s[2:3]
	v_mad_i64_i32 v[0:1], s[10:11], v4, s56, v[0:1]
	s_mov_b64 s[10:11], 0xb00
	s_nop 0
	v_cmp_gt_i64_e32 vcc, s[10:11], v[0:1]
	s_and_saveexec_b64 s[38:39], vcc
	s_cbranch_execz .LBB0_59
	v_ashrrev_i32_e32 v1, 31, v0
	v_lshrrev_b32_e32 v1, 29, v1
	v_add_u32_e32 v1, v0, v1
	v_ashrrev_i32_e32 v6, 3, v1
	v_and_b32_e32 v1, -8, v1
	v_sub_u32_e32 v0, v0, v1
	v_cmp_gt_i32_e32 vcc, 0, v0
	v_mov_b32_e32 v1, 0x161
	v_mov_b32_e32 v5, 0x160
	v_cndmask_b32_e32 v1, v5, v1, vcc
	v_mad_u64_u32 v[0:1], s[10:11], v0, v1, v[6:7]
	s_mov_b32 s6, 0x2e8ba2e9
	v_mul_hi_i32 v1, v0, s6
	v_lshrrev_b32_e32 v5, 31, v1
	v_ashrrev_i32_e32 v1, 9, v1
	v_add_u32_e32 v1, v1, v5
	v_mul_i32_i24_e32 v1, 0xb00, v1
	v_sub_u32_e32 v0, v0, v1
	s_movk_i32 s6, 0xba3
	v_mul_i32_i24_sdwa v1, sext(v0), s6 dst_sel:DWORD dst_unused:UNUSED_PAD src0_sel:WORD_0 src1_sel:DWORD
	v_lshrrev_b32_e32 v5, 31, v1
	v_ashrrev_i32_e32 v1, 19, v1
	v_add_u16_e32 v1, v1, v5
	v_mul_lo_u16_e32 v5, 0xb0, v1
	v_sub_u16_e32 v0, v0, v5
	v_ashrrev_i16_e32 v5, 15, v0
	v_lshrrev_b16_e32 v5, 13, v5
	v_add_u16_e32 v5, v0, v5
	v_and_b32_e32 v5, -8, v5
	v_sub_u16_e32 v0, v0, v5
	v_bfe_i32 v1, v1, 0, 16
	v_bfe_i32 v0, v0, 0, 16
	v_lshl_add_u32 v0, v1, 3, v0
	v_ashrrev_i32_e32 v1, 31, v0
	v_lshlrev_b64 v[0:1], 14, v[0:1]
	v_lshl_add_u64 v[0:1], s[26:27], 0, v[0:1]
	v_lshl_add_u64 v[0:1], v[0:1], 0, v[140:141]
	global_load_dwordx4 v[64:67], v[0:1], off
	global_load_dwordx4 v[68:71], v[0:1], off offset:16
	global_load_dwordx4 v[72:75], v[0:1], off offset:32
	global_load_dwordx4 v[76:79], v[0:1], off offset:48
.LBB0_59:
	s_or_b64 exec, exec, s[38:39]
	v_add_u32_e32 v4, 6, v3
	v_mov_b64_e32 v[0:1], s[2:3]
	v_mad_i64_i32 v[0:1], s[10:11], v4, s56, v[0:1]
	s_mov_b64 s[10:11], 0xb00
	s_nop 0
	v_cmp_gt_i64_e32 vcc, s[10:11], v[0:1]
	s_and_saveexec_b64 s[38:39], vcc
	s_cbranch_execz .LBB0_61
	v_ashrrev_i32_e32 v1, 31, v0
	v_lshrrev_b32_e32 v1, 29, v1
	v_add_u32_e32 v1, v0, v1
	v_ashrrev_i32_e32 v6, 3, v1
	v_and_b32_e32 v1, -8, v1
	v_sub_u32_e32 v0, v0, v1
	v_cmp_gt_i32_e32 vcc, 0, v0
	v_mov_b32_e32 v1, 0x161
	v_mov_b32_e32 v5, 0x160
	v_cndmask_b32_e32 v1, v5, v1, vcc
	v_mad_u64_u32 v[0:1], s[10:11], v0, v1, v[6:7]
	s_mov_b32 s6, 0x2e8ba2e9
	v_mul_hi_i32 v1, v0, s6
	v_lshrrev_b32_e32 v5, 31, v1
	v_ashrrev_i32_e32 v1, 9, v1
	v_add_u32_e32 v1, v1, v5
	v_mul_i32_i24_e32 v1, 0xb00, v1
	v_sub_u32_e32 v0, v0, v1
	s_movk_i32 s6, 0xba3
	v_mul_i32_i24_sdwa v1, sext(v0), s6 dst_sel:DWORD dst_unused:UNUSED_PAD src0_sel:WORD_0 src1_sel:DWORD
	v_lshrrev_b32_e32 v5, 31, v1
	v_ashrrev_i32_e32 v1, 19, v1
	v_add_u16_e32 v1, v1, v5
	v_mul_lo_u16_e32 v5, 0xb0, v1
	v_sub_u16_e32 v0, v0, v5
	v_ashrrev_i16_e32 v5, 15, v0
	v_lshrrev_b16_e32 v5, 13, v5
	v_add_u16_e32 v5, v0, v5
	v_and_b32_e32 v5, -8, v5
	v_sub_u16_e32 v0, v0, v5
	v_bfe_i32 v1, v1, 0, 16
	v_bfe_i32 v0, v0, 0, 16
	v_lshl_add_u32 v0, v1, 3, v0
	v_ashrrev_i32_e32 v1, 31, v0
	v_lshlrev_b64 v[0:1], 14, v[0:1]
	v_lshl_add_u64 v[0:1], s[26:27], 0, v[0:1]
	v_lshl_add_u64 v[0:1], v[0:1], 0, v[140:141]
	global_load_dwordx4 v[80:83], v[0:1], off
	global_load_dwordx4 v[84:87], v[0:1], off offset:16
	global_load_dwordx4 v[88:91], v[0:1], off offset:32
	global_load_dwordx4 v[92:95], v[0:1], off offset:48
.LBB0_61:
	s_or_b64 exec, exec, s[38:39]
	v_add_u32_e32 v4, 8, v3
	v_mov_b64_e32 v[0:1], s[2:3]
	v_mad_i64_i32 v[0:1], s[10:11], v4, s56, v[0:1]
	s_mov_b64 s[10:11], 0xb00
	s_nop 0
	v_cmp_gt_i64_e32 vcc, s[10:11], v[0:1]
	s_and_saveexec_b64 s[38:39], vcc
	s_cbranch_execz .LBB0_63
	v_ashrrev_i32_e32 v1, 31, v0
	v_lshrrev_b32_e32 v1, 29, v1
	v_add_u32_e32 v1, v0, v1
	v_ashrrev_i32_e32 v6, 3, v1
	v_and_b32_e32 v1, -8, v1
	v_sub_u32_e32 v0, v0, v1
	v_cmp_gt_i32_e32 vcc, 0, v0
	v_mov_b32_e32 v1, 0x161
	v_mov_b32_e32 v5, 0x160
	v_cndmask_b32_e32 v1, v5, v1, vcc
	v_mad_u64_u32 v[0:1], s[10:11], v0, v1, v[6:7]
	s_mov_b32 s6, 0x2e8ba2e9
	v_mul_hi_i32 v1, v0, s6
	v_lshrrev_b32_e32 v5, 31, v1
	v_ashrrev_i32_e32 v1, 9, v1
	v_add_u32_e32 v1, v1, v5
	v_mul_i32_i24_e32 v1, 0xb00, v1
	v_sub_u32_e32 v0, v0, v1
	s_movk_i32 s6, 0xba3
	v_mul_i32_i24_sdwa v1, sext(v0), s6 dst_sel:DWORD dst_unused:UNUSED_PAD src0_sel:WORD_0 src1_sel:DWORD
	v_lshrrev_b32_e32 v5, 31, v1
	v_ashrrev_i32_e32 v1, 19, v1
	v_add_u16_e32 v1, v1, v5
	v_mul_lo_u16_e32 v5, 0xb0, v1
	v_sub_u16_e32 v0, v0, v5
	v_ashrrev_i16_e32 v5, 15, v0
	v_lshrrev_b16_e32 v5, 13, v5
	v_add_u16_e32 v5, v0, v5
	v_and_b32_e32 v5, -8, v5
	v_sub_u16_e32 v0, v0, v5
	v_bfe_i32 v1, v1, 0, 16
	v_bfe_i32 v0, v0, 0, 16
	v_lshl_add_u32 v0, v1, 3, v0
	v_ashrrev_i32_e32 v1, 31, v0
	v_lshlrev_b64 v[0:1], 14, v[0:1]
	v_lshl_add_u64 v[0:1], s[26:27], 0, v[0:1]
	v_lshl_add_u64 v[0:1], v[0:1], 0, v[140:141]
	global_load_dwordx4 v[96:99], v[0:1], off
	global_load_dwordx4 v[100:103], v[0:1], off offset:16
	global_load_dwordx4 v[104:107], v[0:1], off offset:32
	global_load_dwordx4 v[108:111], v[0:1], off offset:48
.LBB0_63:
	s_or_b64 exec, exec, s[38:39]
	v_add_u32_e32 v4, 10, v3
	v_mov_b64_e32 v[0:1], s[2:3]
	v_mad_i64_i32 v[0:1], s[10:11], v4, s56, v[0:1]
	s_mov_b64 s[10:11], 0xb00
	s_nop 0
	v_cmp_gt_i64_e32 vcc, s[10:11], v[0:1]
	s_and_saveexec_b64 s[38:39], vcc
	s_cbranch_execz .LBB0_65
	v_ashrrev_i32_e32 v1, 31, v0
	v_lshrrev_b32_e32 v1, 29, v1
	v_add_u32_e32 v1, v0, v1
	v_ashrrev_i32_e32 v6, 3, v1
	v_and_b32_e32 v1, -8, v1
	v_sub_u32_e32 v0, v0, v1
	v_cmp_gt_i32_e32 vcc, 0, v0
	v_mov_b32_e32 v1, 0x161
	v_mov_b32_e32 v5, 0x160
	v_cndmask_b32_e32 v1, v5, v1, vcc
	v_mad_u64_u32 v[0:1], s[10:11], v0, v1, v[6:7]
	s_mov_b32 s6, 0x2e8ba2e9
	v_mul_hi_i32 v1, v0, s6
	v_lshrrev_b32_e32 v5, 31, v1
	v_ashrrev_i32_e32 v1, 9, v1
	v_add_u32_e32 v1, v1, v5
	v_mul_i32_i24_e32 v1, 0xb00, v1
	v_sub_u32_e32 v0, v0, v1
	s_movk_i32 s6, 0xba3
	v_mul_i32_i24_sdwa v1, sext(v0), s6 dst_sel:DWORD dst_unused:UNUSED_PAD src0_sel:WORD_0 src1_sel:DWORD
	v_lshrrev_b32_e32 v5, 31, v1
	v_ashrrev_i32_e32 v1, 19, v1
	v_add_u16_e32 v1, v1, v5
	v_mul_lo_u16_e32 v5, 0xb0, v1
	v_sub_u16_e32 v0, v0, v5
	v_ashrrev_i16_e32 v5, 15, v0
	v_lshrrev_b16_e32 v5, 13, v5
	v_add_u16_e32 v5, v0, v5
	v_and_b32_e32 v5, -8, v5
	v_sub_u16_e32 v0, v0, v5
	v_bfe_i32 v1, v1, 0, 16
	v_bfe_i32 v0, v0, 0, 16
	v_lshl_add_u32 v0, v1, 3, v0
	v_ashrrev_i32_e32 v1, 31, v0
	v_lshlrev_b64 v[0:1], 14, v[0:1]
	v_lshl_add_u64 v[0:1], s[26:27], 0, v[0:1]
	v_lshl_add_u64 v[0:1], v[0:1], 0, v[140:141]
	global_load_dwordx4 v[112:115], v[0:1], off
	global_load_dwordx4 v[116:119], v[0:1], off offset:16
	global_load_dwordx4 v[120:123], v[0:1], off offset:32
	global_load_dwordx4 v[124:127], v[0:1], off offset:48
.LBB0_65:
	s_or_b64 exec, exec, s[38:39]
	v_add_u32_e32 v4, 12, v3
	v_mov_b64_e32 v[0:1], s[2:3]
	v_mad_i64_i32 v[0:1], s[10:11], v4, s56, v[0:1]
	s_mov_b64 s[10:11], 0xb00
	s_nop 0
	v_cmp_gt_i64_e32 vcc, s[10:11], v[0:1]
	s_and_saveexec_b64 s[38:39], vcc
	s_cbranch_execz .LBB0_67
	v_ashrrev_i32_e32 v1, 31, v0
	v_lshrrev_b32_e32 v1, 29, v1
	v_add_u32_e32 v1, v0, v1
	v_ashrrev_i32_e32 v6, 3, v1
	v_and_b32_e32 v1, -8, v1
	v_sub_u32_e32 v0, v0, v1
	v_cmp_gt_i32_e32 vcc, 0, v0
	v_mov_b32_e32 v1, 0x161
	v_mov_b32_e32 v5, 0x160
	v_cndmask_b32_e32 v1, v5, v1, vcc
	v_mad_u64_u32 v[0:1], s[10:11], v0, v1, v[6:7]
	s_mov_b32 s6, 0x2e8ba2e9
	v_mul_hi_i32 v1, v0, s6
	v_lshrrev_b32_e32 v5, 31, v1
	v_ashrrev_i32_e32 v1, 9, v1
	v_add_u32_e32 v1, v1, v5
	v_mul_i32_i24_e32 v1, 0xb00, v1
	v_sub_u32_e32 v0, v0, v1
	s_movk_i32 s6, 0xba3
	v_mul_i32_i24_sdwa v1, sext(v0), s6 dst_sel:DWORD dst_unused:UNUSED_PAD src0_sel:WORD_0 src1_sel:DWORD
	v_lshrrev_b32_e32 v5, 31, v1
	v_ashrrev_i32_e32 v1, 19, v1
	v_add_u16_e32 v1, v1, v5
	v_mul_lo_u16_e32 v5, 0xb0, v1
	v_sub_u16_e32 v0, v0, v5
	v_ashrrev_i16_e32 v5, 15, v0
	v_lshrrev_b16_e32 v5, 13, v5
	v_add_u16_e32 v5, v0, v5
	v_and_b32_e32 v5, -8, v5
	v_sub_u16_e32 v0, v0, v5
	v_bfe_i32 v1, v1, 0, 16
	v_bfe_i32 v0, v0, 0, 16
	v_lshl_add_u32 v0, v1, 3, v0
	v_ashrrev_i32_e32 v1, 31, v0
	v_lshlrev_b64 v[0:1], 14, v[0:1]
	v_lshl_add_u64 v[0:1], s[26:27], 0, v[0:1]
	v_lshl_add_u64 v[0:1], v[0:1], 0, v[140:141]
	global_load_dwordx4 v[146:149], v[0:1], off
	global_load_dwordx4 v[150:153], v[0:1], off offset:16
	global_load_dwordx4 v[154:157], v[0:1], off offset:32
	global_load_dwordx4 v[158:161], v[0:1], off offset:48
.LBB0_67:
	s_or_b64 exec, exec, s[38:39]
	v_add_u32_e32 v3, 14, v3
	v_mov_b64_e32 v[0:1], s[2:3]
	v_mad_i64_i32 v[0:1], s[10:11], v3, s56, v[0:1]
	s_mov_b64 s[10:11], 0xb00
	s_nop 0
	v_cmp_gt_i64_e32 vcc, s[10:11], v[0:1]
	s_and_saveexec_b64 s[38:39], vcc
	s_cbranch_execz .LBB0_69
	v_ashrrev_i32_e32 v1, 31, v0
	v_lshrrev_b32_e32 v1, 29, v1
	v_add_u32_e32 v1, v0, v1
	v_ashrrev_i32_e32 v4, 3, v1
	v_and_b32_e32 v1, -8, v1
	v_sub_u32_e32 v0, v0, v1
	v_cmp_gt_i32_e32 vcc, 0, v0
	v_mov_b32_e32 v1, 0x161
	v_mov_b32_e32 v5, 0x160
	v_cndmask_b32_e32 v1, v5, v1, vcc
	v_mad_u64_u32 v[0:1], s[10:11], v0, v1, v[4:5]
	s_mov_b32 s6, 0x2e8ba2e9
	v_mul_hi_i32 v1, v0, s6
	v_lshrrev_b32_e32 v4, 31, v1
	v_ashrrev_i32_e32 v1, 9, v1
	v_add_u32_e32 v1, v1, v4
	v_mul_i32_i24_e32 v1, 0xb00, v1
	v_sub_u32_e32 v0, v0, v1
	s_movk_i32 s6, 0xba3
	v_mul_i32_i24_sdwa v1, sext(v0), s6 dst_sel:DWORD dst_unused:UNUSED_PAD src0_sel:WORD_0 src1_sel:DWORD
	v_lshrrev_b32_e32 v4, 31, v1
	v_ashrrev_i32_e32 v1, 19, v1
	v_add_u16_e32 v1, v1, v4
	v_mul_lo_u16_e32 v4, 0xb0, v1
	v_sub_u16_e32 v0, v0, v4
	v_ashrrev_i16_e32 v4, 15, v0
	v_lshrrev_b16_e32 v4, 13, v4
	v_add_u16_e32 v4, v0, v4
	v_and_b32_e32 v4, -8, v4
	v_sub_u16_e32 v0, v0, v4
	v_bfe_i32 v1, v1, 0, 16
	v_bfe_i32 v0, v0, 0, 16
	v_lshl_add_u32 v0, v1, 3, v0
	v_ashrrev_i32_e32 v1, 31, v0
	v_lshlrev_b64 v[0:1], 14, v[0:1]
	v_lshl_add_u64 v[0:1], s[26:27], 0, v[0:1]
	v_lshl_add_u64 v[0:1], v[0:1], 0, v[140:141]
	global_load_dwordx4 v[162:165], v[0:1], off
	global_load_dwordx4 v[166:169], v[0:1], off offset:16
	global_load_dwordx4 v[170:173], v[0:1], off offset:32
	global_load_dwordx4 v[174:177], v[0:1], off offset:48
.LBB0_69:
	s_or_b64 exec, exec, s[38:39]
	s_waitcnt vmcnt(0)
	v_add_u32_e32 v3, -14, v3
	v_mov_b32_e32 v4, v3
	v_mov_b64_e32 v[0:1], s[2:3]
	v_mad_i64_i32 v[0:1], s[10:11], v4, s56, v[0:1]
	s_mov_b64 s[10:11], 0xb00
	s_nop 0
	v_cmp_gt_i64_e32 vcc, s[10:11], v[0:1]
	s_and_saveexec_b64 s[38:39], vcc
	s_cbranch_execz my_rs0_0
	v_pk_add_f32 v[0:1], v[34:35], v[38:39]
	v_pk_add_f32 v[32:33], v[32:33], v[36:37]
	v_pk_add_f32 v[34:35], v[42:43], v[46:47]
	v_pk_add_f32 v[36:37], v[40:41], v[44:45]
	v_pk_add_f32 v[0:1], v[0:1], v[34:35]
	v_pk_add_f32 v[32:33], v[32:33], v[36:37]
	s_nop 0
	v_pk_mov_b32 v[34:35], v[32:33], v[0:1] op_sel:[1,0]
	v_mov_b32_e32 v33, v1
	v_pk_add_f32 v[0:1], v[34:35], v[32:33]
	s_nop 0
	v_add_f32_e32 v0, v0, v1
	v_fmamk_f32 v0, v0, 0x3a800000, v187
	v_mul_f32_e32 v1, 0x4b800000, v0
	v_cmp_gt_f32_e32 vcc, s78, v0
	s_nop 1
	v_cndmask_b32_e32 v0, v0, v1, vcc
	v_rsq_f32_e32 v0, v0
	s_nop 0
	v_mul_f32_e32 v1, 0x45800000, v0
	v_cndmask_b32_e32 v0, v0, v1, vcc
	v_lshl_add_u32 v1, v3, 10, v2
	ds_write_b32 v1, v0
my_rs0_0:
	s_or_b64 exec, exec, s[38:39]
	v_add_u32_e32 v4, 2, v3
	v_mov_b64_e32 v[0:1], s[2:3]
	v_mad_i64_i32 v[0:1], s[10:11], v4, s56, v[0:1]
	s_mov_b64 s[10:11], 0xb00
	s_nop 0
	v_cmp_gt_i64_e32 vcc, s[10:11], v[0:1]
	s_and_saveexec_b64 s[38:39], vcc
	s_cbranch_execz my_rs0_1
	v_pk_add_f32 v[0:1], v[50:51], v[54:55]
	v_pk_add_f32 v[6:7], v[48:49], v[52:53]
	v_pk_add_f32 v[48:49], v[58:59], v[62:63]
	v_pk_add_f32 v[50:51], v[56:57], v[60:61]
	v_pk_add_f32 v[0:1], v[0:1], v[48:49]
	v_pk_add_f32 v[6:7], v[6:7], v[50:51]
	s_nop 0
	v_pk_mov_b32 v[48:49], v[6:7], v[0:1] op_sel:[1,0]
	v_mov_b32_e32 v7, v1
	v_pk_add_f32 v[0:1], v[48:49], v[6:7]
	s_nop 0
	v_add_f32_e32 v0, v0, v1
	v_fmamk_f32 v0, v0, 0x3a800000, v187
	v_mul_f32_e32 v1, 0x4b800000, v0
	v_cmp_gt_f32_e32 vcc, s78, v0
	s_nop 1
	v_cndmask_b32_e32 v0, v0, v1, vcc
	v_rsq_f32_e32 v0, v0
	s_nop 0
	v_mul_f32_e32 v1, 0x45800000, v0
	v_cndmask_b32_e32 v0, v0, v1, vcc
	v_lshl_add_u32 v1, v4, 10, v2
	ds_write_b32 v1, v0
my_rs0_1:
	s_or_b64 exec, exec, s[38:39]
	v_add_u32_e32 v4, 4, v3
	v_mov_b64_e32 v[0:1], s[2:3]
	v_mad_i64_i32 v[0:1], s[10:11], v4, s56, v[0:1]
	s_mov_b64 s[10:11], 0xb00
	s_nop 0
	v_cmp_gt_i64_e32 vcc, s[10:11], v[0:1]
	s_and_saveexec_b64 s[38:39], vcc
	s_cbranch_execz my_rs0_2
	v_pk_add_f32 v[0:1], v[66:67], v[70:71]
	v_pk_add_f32 v[6:7], v[64:65], v[68:69]
	v_pk_add_f32 v[64:65], v[74:75], v[78:79]
	v_pk_add_f32 v[66:67], v[72:73], v[76:77]
	v_pk_add_f32 v[0:1], v[0:1], v[64:65]
	v_pk_add_f32 v[6:7], v[6:7], v[66:67]
	s_nop 0
	v_pk_mov_b32 v[64:65], v[6:7], v[0:1] op_sel:[1,0]
	v_mov_b32_e32 v7, v1
	v_pk_add_f32 v[0:1], v[64:65], v[6:7]
	s_nop 0
	v_add_f32_e32 v0, v0, v1
	v_fmamk_f32 v0, v0, 0x3a800000, v187
	v_mul_f32_e32 v1, 0x4b800000, v0
	v_cmp_gt_f32_e32 vcc, s78, v0
	s_nop 1
	v_cndmask_b32_e32 v0, v0, v1, vcc
	v_rsq_f32_e32 v0, v0
	s_nop 0
	v_mul_f32_e32 v1, 0x45800000, v0
	v_cndmask_b32_e32 v0, v0, v1, vcc
	v_lshl_add_u32 v1, v4, 10, v2
	ds_write_b32 v1, v0
my_rs0_2:
	s_or_b64 exec, exec, s[38:39]
	v_add_u32_e32 v4, 6, v3
	v_mov_b64_e32 v[0:1], s[2:3]
	v_mad_i64_i32 v[0:1], s[10:11], v4, s56, v[0:1]
	s_mov_b64 s[10:11], 0xb00
	s_nop 0
	v_cmp_gt_i64_e32 vcc, s[10:11], v[0:1]
	s_and_saveexec_b64 s[38:39], vcc
	s_cbranch_execz my_rs0_3
	v_pk_add_f32 v[0:1], v[82:83], v[86:87]
	v_pk_add_f32 v[6:7], v[80:81], v[84:85]
	v_pk_add_f32 v[80:81], v[90:91], v[94:95]
	v_pk_add_f32 v[82:83], v[88:89], v[92:93]
	v_pk_add_f32 v[0:1], v[0:1], v[80:81]
	v_pk_add_f32 v[6:7], v[6:7], v[82:83]
	s_nop 0
	v_pk_mov_b32 v[80:81], v[6:7], v[0:1] op_sel:[1,0]
	v_mov_b32_e32 v7, v1
	v_pk_add_f32 v[0:1], v[80:81], v[6:7]
	s_nop 0
	v_add_f32_e32 v0, v0, v1
	v_fmamk_f32 v0, v0, 0x3a800000, v187
	v_mul_f32_e32 v1, 0x4b800000, v0
	v_cmp_gt_f32_e32 vcc, s78, v0
	s_nop 1
	v_cndmask_b32_e32 v0, v0, v1, vcc
	v_rsq_f32_e32 v0, v0
	s_nop 0
	v_mul_f32_e32 v1, 0x45800000, v0
	v_cndmask_b32_e32 v0, v0, v1, vcc
	v_lshl_add_u32 v1, v4, 10, v2
	ds_write_b32 v1, v0
my_rs0_3:
	s_or_b64 exec, exec, s[38:39]
	v_add_u32_e32 v4, 8, v3
	v_mov_b64_e32 v[0:1], s[2:3]
	v_mad_i64_i32 v[0:1], s[10:11], v4, s56, v[0:1]
	s_mov_b64 s[10:11], 0xb00
	s_nop 0
	v_cmp_gt_i64_e32 vcc, s[10:11], v[0:1]
	s_and_saveexec_b64 s[38:39], vcc
	s_cbranch_execz my_rs0_4
	v_pk_add_f32 v[0:1], v[98:99], v[102:103]
	v_pk_add_f32 v[6:7], v[96:97], v[100:101]
	v_pk_add_f32 v[96:97], v[106:107], v[110:111]
	v_pk_add_f32 v[98:99], v[104:105], v[108:109]
	v_pk_add_f32 v[0:1], v[0:1], v[96:97]
	v_pk_add_f32 v[6:7], v[6:7], v[98:99]
	s_nop 0
	v_pk_mov_b32 v[96:97], v[6:7], v[0:1] op_sel:[1,0]
	v_mov_b32_e32 v7, v1
	v_pk_add_f32 v[0:1], v[96:97], v[6:7]
	s_nop 0
	v_add_f32_e32 v0, v0, v1
	v_fmamk_f32 v0, v0, 0x3a800000, v187
	v_mul_f32_e32 v1, 0x4b800000, v0
	v_cmp_gt_f32_e32 vcc, s78, v0
	s_nop 1
	v_cndmask_b32_e32 v0, v0, v1, vcc
	v_rsq_f32_e32 v0, v0
	s_nop 0
	v_mul_f32_e32 v1, 0x45800000, v0
	v_cndmask_b32_e32 v0, v0, v1, vcc
	v_lshl_add_u32 v1, v4, 10, v2
	ds_write_b32 v1, v0
my_rs0_4:
	s_or_b64 exec, exec, s[38:39]
	v_add_u32_e32 v4, 10, v3
	v_mov_b64_e32 v[0:1], s[2:3]
	v_mad_i64_i32 v[0:1], s[10:11], v4, s56, v[0:1]
	s_mov_b64 s[10:11], 0xb00
	s_nop 0
	v_cmp_gt_i64_e32 vcc, s[10:11], v[0:1]
	s_and_saveexec_b64 s[38:39], vcc
	s_cbranch_execz my_rs0_5
	v_pk_add_f32 v[0:1], v[114:115], v[118:119]
	v_pk_add_f32 v[6:7], v[112:113], v[116:117]
	v_pk_add_f32 v[112:113], v[122:123], v[126:127]
	v_pk_add_f32 v[114:115], v[120:121], v[124:125]
	v_pk_add_f32 v[0:1], v[0:1], v[112:113]
	v_pk_add_f32 v[6:7], v[6:7], v[114:115]
	s_nop 0
	v_pk_mov_b32 v[112:113], v[6:7], v[0:1] op_sel:[1,0]
	v_mov_b32_e32 v7, v1
	v_pk_add_f32 v[0:1], v[112:113], v[6:7]
	s_nop 0
	v_add_f32_e32 v0, v0, v1
	v_fmamk_f32 v0, v0, 0x3a800000, v187
	v_mul_f32_e32 v1, 0x4b800000, v0
	v_cmp_gt_f32_e32 vcc, s78, v0
	s_nop 1
	v_cndmask_b32_e32 v0, v0, v1, vcc
	v_rsq_f32_e32 v0, v0
	s_nop 0
	v_mul_f32_e32 v1, 0x45800000, v0
	v_cndmask_b32_e32 v0, v0, v1, vcc
	v_lshl_add_u32 v1, v4, 10, v2
	ds_write_b32 v1, v0
my_rs0_5:
	s_or_b64 exec, exec, s[38:39]
	v_add_u32_e32 v4, 12, v3
	v_mov_b64_e32 v[0:1], s[2:3]
	v_mad_i64_i32 v[0:1], s[10:11], v4, s56, v[0:1]
	s_mov_b64 s[10:11], 0xb00
	s_nop 0
	v_cmp_gt_i64_e32 vcc, s[10:11], v[0:1]
	s_and_saveexec_b64 s[38:39], vcc
	s_cbranch_execz my_rs0_6
	v_pk_add_f32 v[0:1], v[148:149], v[152:153]
	v_pk_add_f32 v[6:7], v[146:147], v[150:151]
	v_pk_add_f32 v[146:147], v[156:157], v[160:161]
	v_pk_add_f32 v[148:149], v[154:155], v[158:159]
	v_pk_add_f32 v[0:1], v[0:1], v[146:147]
	v_pk_add_f32 v[6:7], v[6:7], v[148:149]
	s_nop 0
	v_pk_mov_b32 v[146:147], v[6:7], v[0:1] op_sel:[1,0]
	v_mov_b32_e32 v7, v1
	v_pk_add_f32 v[0:1], v[146:147], v[6:7]
	s_nop 0
	v_add_f32_e32 v0, v0, v1
	v_fmamk_f32 v0, v0, 0x3a800000, v187
	v_mul_f32_e32 v1, 0x4b800000, v0
	v_cmp_gt_f32_e32 vcc, s78, v0
	s_nop 1
	v_cndmask_b32_e32 v0, v0, v1, vcc
	v_rsq_f32_e32 v0, v0
	s_nop 0
	v_mul_f32_e32 v1, 0x45800000, v0
	v_cndmask_b32_e32 v0, v0, v1, vcc
	v_lshl_add_u32 v1, v4, 10, v2
	ds_write_b32 v1, v0
my_rs0_6:
	s_or_b64 exec, exec, s[38:39]
	v_add_u32_e32 v3, 14, v3
	v_mov_b64_e32 v[0:1], s[2:3]
	v_mad_i64_i32 v[0:1], s[10:11], v3, s56, v[0:1]
	s_mov_b64 s[10:11], 0xb00
	s_nop 0
	v_cmp_gt_i64_e32 vcc, s[10:11], v[0:1]
	s_and_saveexec_b64 s[38:39], vcc
	s_cbranch_execz my_rs0_7
	v_pk_add_f32 v[0:1], v[164:165], v[168:169]
	v_pk_add_f32 v[162:163], v[162:163], v[166:167]
	v_pk_add_f32 v[164:165], v[172:173], v[176:177]
	v_pk_add_f32 v[166:167], v[170:171], v[174:175]
	v_pk_add_f32 v[0:1], v[0:1], v[164:165]
	v_pk_add_f32 v[162:163], v[162:163], v[166:167]
	s_nop 0
	v_pk_mov_b32 v[164:165], v[162:163], v[0:1] op_sel:[1,0]
	v_mov_b32_e32 v163, v1
	v_pk_add_f32 v[0:1], v[164:165], v[162:163]
	s_nop 0
	v_add_f32_e32 v0, v0, v1
	v_fmamk_f32 v0, v0, 0x3a800000, v187
	v_mul_f32_e32 v1, 0x4b800000, v0
	v_cmp_gt_f32_e32 vcc, s78, v0
	s_nop 1
	v_cndmask_b32_e32 v0, v0, v1, vcc
	v_rsq_f32_e32 v0, v0
	s_nop 0
	v_mul_f32_e32 v1, 0x45800000, v0
	v_cndmask_b32_e32 v0, v0, v1, vcc
	v_lshl_add_u32 v1, v3, 10, v2
	ds_write_b32 v1, v0
my_rs0_7:
	s_or_b64 exec, exec, s[38:39]
	v_readlane_b32 s10, v252, 21
	v_readlane_b32 s11, v252, 22
	s_andn2_b64 vcc, exec, s[10:11]
	s_waitcnt lgkmcnt(0)
	s_barrier
	s_cbranch_vccnz .LBB0_83
	v_ashrrev_i32_e32 v1, 31, v8
	v_lshrrev_b32_e32 v1, 26, v1
	v_add_u32_e32 v1, v8, v1
	v_ashrrev_i32_e32 v9, 6, v1
	v_bfe_i32 v1, v8, 27, 1
	v_lshlrev_b32_e32 v0, 4, v8
	v_lshrrev_b32_e32 v1, 22, v1
	v_add_u32_e32 v1, v0, v1
	v_and_b32_e32 v1, 0xfffffc00, v1
	v_sub_u32_e32 v1, v0, v1
	v_lshrrev_b32_e32 v2, 4, v1
	v_bitop3_b32 v2, v2, v1, 32 bitop3:0x6c
	v_ashrrev_i32_e32 v1, 31, v1
	v_lshrrev_b32_e32 v1, 26, v1
	v_add_u32_e32 v1, v2, v1
	v_ashrrev_i32_e32 v10, 6, v1
	v_lshlrev_b32_e32 v3, 3, v9
	v_mul_i32_i24_e32 v4, 64, v10
	v_and_b32_e32 v3, -16, v3
	v_sub_u32_e32 v2, v2, v4
	v_mov_b32_e32 v6, 1
	v_add_u32_e32 v1, v10, v3
	v_lshlrev_b32_e32 v3, 5, v9
	v_ashrrev_i16_sdwa v2, v6, sext(v2) dst_sel:DWORD dst_unused:UNUSED_PAD src0_sel:DWORD src1_sel:BYTE_0
	v_and_b32_e32 v3, 32, v3
	v_bfe_i32 v11, v2, 0, 16
	v_and_b32_e32 v5, 3, v10
	s_mov_b32 s10, 0x1fffe0
	v_add_lshl_u32 v3, v3, v11, 1
	v_add_u32_e32 v0, 0x2000, v0
	v_lshlrev_b32_e32 v2, 1, v1
	v_lshrrev_b32_e32 v4, 2, v1
	v_and_or_b32 v5, v1, s10, v5
	v_lshl_add_u32 v128, v1, 11, v3
	v_ashrrev_i32_e32 v1, 31, v0
	v_lshrrev_b32_e32 v1, 22, v1
	v_add_u32_e32 v1, v0, v1
	v_ashrrev_i32_e32 v12, 10, v1
	v_mul_i32_i24_e32 v1, 0x400, v12
	v_sub_u32_e32 v0, v0, v1
	v_and_b32_e32 v2, 24, v2
	v_and_b32_e32 v4, 4, v4
	v_lshrrev_b32_e32 v1, 4, v0
	v_or3_b32 v2, v5, v4, v2
	v_bitop3_b32 v0, v1, v0, 32 bitop3:0x6c
	v_lshl_add_u32 v140, v2, 11, v3
	v_ashrrev_i32_e32 v2, 31, v0
	v_lshrrev_b32_e32 v2, 26, v2
	s_add_u32 s33, s34, 0x12290000
	v_lshlrev_b32_e32 v1, 3, v12
	v_add_u32_e32 v2, v0, v2
	s_addc_u32 s41, s35, 0
	v_and_b32_e32 v1, -16, v1
	v_ashrrev_i32_e32 v13, 6, v2
	s_add_u32 s57, s30, 0x2200000
	v_add_u32_e32 v1, v13, v1
	v_and_b32_e32 v4, 3, v13
	s_addc_u32 s58, s31, 0
	v_and_b32_e32 v2, 0xc0, v2
	v_and_or_b32 v4, v1, s10, v4
	s_ashr_i32 s10, s9, 6
	s_ashr_i32 s6, s9, 8
	v_sub_u32_e32 v0, v0, v2
	s_lshl_b32 s59, s10, 10
	v_readlane_b32 s26, v253, 50
	v_ashrrev_i16_sdwa v0, v6, sext(v0) dst_sel:DWORD dst_unused:UNUSED_PAD src0_sel:DWORD src1_sel:BYTE_0
	v_readlane_b32 s27, v253, 51
	s_add_u32 s50, s57, s26
	v_lshlrev_b32_e32 v3, 5, v12
	v_bfe_i32 v14, v0, 0, 16
	v_lshlrev_b32_e32 v0, 1, v1
	v_lshrrev_b32_e32 v2, 2, v1
	s_addc_u32 s51, s58, s27
	s_add_i32 s68, s59, 0
	v_and_b32_e32 v3, 32, v3
	v_and_b32_e32 v0, 24, v0
	v_and_b32_e32 v2, 4, v2
	s_add_i32 m0, s68, 0x10000
	v_or3_b32 v0, v4, v2, v0
	v_add_lshl_u32 v2, v3, v14, 1
	global_load_lds_dwordx4 v140, s[50:51]
	s_add_i32 m0, s68, 0x12000
	v_readlane_b32 s26, v254, 2
	v_lshl_add_u32 v132, v0, 11, v2
	v_readlane_b32 s27, v254, 3
	s_add_u32 s26, s33, s26
	global_load_lds_dwordx4 v132, s[50:51]
	s_addc_u32 s27, s41, s27
	s_mov_b32 m0, s68
	s_add_i32 s69, s68, 0x2000
	v_lshl_add_u32 v130, v1, 11, v2
	global_load_lds_dwordx4 v128, s[26:27]
	s_mov_b32 m0, s69
	s_add_u32 s30, s50, 0x40000
	global_load_lds_dwordx4 v130, s[26:27]
	s_addc_u32 s31, s51, 0
	s_add_i32 m0, s68, 0x14000
	v_mov_b32_e32 v133, v141
	global_load_lds_dwordx4 v140, s[30:31]
	s_add_i32 m0, s68, 0x16000
	v_mov_b32_e32 v129, v141
	global_load_lds_dwordx4 v132, s[30:31]
	s_add_u32 s30, s26, 0x40000
	s_addc_u32 s31, s27, 0
	s_add_i32 s70, s68, 0x4000
	s_mov_b32 m0, s70
	s_add_i32 s71, s68, 0x6000
	global_load_lds_dwordx4 v128, s[30:31]
	s_mov_b32 m0, s71
	v_mov_b32_e32 v131, v141
	global_load_lds_dwordx4 v130, s[30:31]
	v_lshl_add_u64 v[6:7], s[50:51], 0, v[140:141]
	v_lshl_add_u64 v[4:5], s[50:51], 0, v[132:133]
	v_lshl_add_u64 v[2:3], s[26:27], 0, v[128:129]
	s_cmp_lg_u32 s6, 1
	v_lshl_add_u64 v[0:1], s[26:27], 0, v[130:131]
	s_cbranch_scc1 .LBB0_72
	s_barrier

.LBB0_269:
	s_andn2_b64 vcc, exec, s[26:27]
	s_cbranch_vccnz .LBB0_322
	s_cmp_eq_u32 s60, 6
	s_mov_b64 s[4:5], -1
	s_cbranch_scc0 .LBB0_322
	s_mov_b64 s[26:27], s[0:1]
	s_mov_b64 s[28:29], s[0:1]
	s_mov_b64 s[34:35], s[0:1]
	s_mov_b64 s[4:5], s[0:1]
	s_load_dwordx2 s[4:5], s[4:5], 0xf8
	v_mov_b32_e32 v8, v186
	s_waitcnt lgkmcnt(0)
	v_mov_b64_e32 v[0:1], s[2:3]
	v_ashrrev_i32_e32 v3, 8, v8
	v_mad_i64_i32 v[0:1], s[10:11], v3, s56, v[0:1]
	s_add_u32 s4, s4, 0x1e114000
	v_and_b32_e32 v4, 0xff, v8
	v_readlane_b32 s6, v254, 59
	s_mov_b64 s[10:11], 0x780
	s_addc_u32 s5, s5, 0
	v_readfirstlane_b32 s9, v8
	v_lshl_add_u32 v2, v4, 2, s6
	v_cmp_gt_i64_e32 vcc, s[10:11], v[0:1]
	v_lshlrev_b32_e32 v140, 6, v4
	s_and_saveexec_b64 s[30:31], vcc
	s_cbranch_execz .LBB0_273
	v_ashrrev_i32_e32 v1, 31, v0
	v_lshrrev_b32_e32 v1, 29, v1
	v_add_u32_e32 v1, v0, v1
	v_ashrrev_i32_e32 v4, 3, v1
	v_and_b32_e32 v1, -8, v1
	v_sub_u32_e32 v0, v0, v1
	v_cmp_gt_i32_e32 vcc, 0, v0
	v_mov_b32_e32 v1, 0xf0
	v_mov_b32_e32 v5, 0xf1
	v_cndmask_b32_e32 v1, v1, v5, vcc
	v_mad_u64_u32 v[0:1], s[10:11], v0, v1, v[4:5]
	s_mov_b32 s6, 0x88888889
	v_mul_hi_i32 v1, v0, s6
	v_add_u32_e32 v1, v1, v0
	v_lshrrev_b32_e32 v4, 31, v1
	v_ashrrev_i32_e32 v1, 10, v1
	v_add_u32_e32 v1, v1, v4
	v_mul_i32_i24_e32 v1, 0x780, v1
	v_sub_u32_e32 v0, v0, v1
	s_movk_i32 s6, 0x8889
	v_mul_i32_i24_sdwa v1, sext(v0), s6 dst_sel:DWORD dst_unused:UNUSED_PAD src0_sel:WORD_0 src1_sel:DWORD
	v_add_u16_sdwa v1, v1, v0 dst_sel:DWORD dst_unused:UNUSED_PAD src0_sel:WORD_1 src1_sel:DWORD
	v_lshrrev_b16_e32 v4, 15, v1
	v_ashrrev_i16_e32 v1, 6, v1
	v_add_u16_e32 v1, v1, v4
	v_mul_lo_u16_e32 v4, 0x78, v1
	v_sub_u16_e32 v0, v0, v4
	v_mov_b32_e32 v4, 12
	v_lshrrev_b16_sdwa v4, v4, sext(v0) dst_sel:DWORD dst_unused:UNUSED_PAD src0_sel:DWORD src1_sel:BYTE_0
	v_and_b32_e32 v4, 7, v4
	v_add_u16_e32 v4, v0, v4
	v_and_b32_e32 v4, 0xf8, v4
	v_sub_u16_e32 v0, v0, v4
	v_bfe_i32 v1, v1, 0, 16
	v_bfe_i32 v0, v0, 0, 8
	v_lshl_add_u32 v0, v1, 3, v0
	v_ashrrev_i32_e32 v1, 31, v0
	v_lshlrev_b64 v[0:1], 14, v[0:1]
	v_lshl_add_u64 v[0:1], s[4:5], 0, v[0:1]
	v_lshl_add_u64 v[0:1], v[0:1], 0, v[140:141]
	global_load_dwordx4 v[32:35], v[0:1], off
	global_load_dwordx4 v[36:39], v[0:1], off offset:16
	global_load_dwordx4 v[40:43], v[0:1], off offset:32
	global_load_dwordx4 v[44:47], v[0:1], off offset:48
.LBB0_273:
	s_or_b64 exec, exec, s[30:31]
	s_load_dwordx2 s[30:31], s[26:27], 0xf8
	s_nop 0
	s_load_dwordx2 s[28:29], s[28:29], 0xf8
	s_nop 0
	s_load_dwordx2 s[26:27], s[34:35], 0xf8
	v_add_u32_e32 v4, 2, v3
	v_mov_b64_e32 v[0:1], s[2:3]
	v_mad_i64_i32 v[0:1], s[10:11], v4, s56, v[0:1]
	s_mov_b64 s[10:11], 0x780
	s_nop 0
	v_cmp_gt_i64_e32 vcc, s[10:11], v[0:1]
	s_and_saveexec_b64 s[34:35], vcc
	s_cbranch_execz .LBB0_275
	v_ashrrev_i32_e32 v1, 31, v0
	v_lshrrev_b32_e32 v1, 29, v1
	v_add_u32_e32 v1, v0, v1
	v_ashrrev_i32_e32 v6, 3, v1
	v_and_b32_e32 v1, -8, v1
	v_sub_u32_e32 v0, v0, v1
	v_cmp_gt_i32_e32 vcc, 0, v0
	v_mov_b32_e32 v1, 0xf0
	v_mov_b32_e32 v5, 0xf1
	v_cndmask_b32_e32 v1, v1, v5, vcc
	v_mad_u64_u32 v[0:1], s[10:11], v0, v1, v[6:7]
	s_mov_b32 s6, 0x88888889
	v_mul_hi_i32 v1, v0, s6
	v_add_u32_e32 v1, v1, v0
	v_lshrrev_b32_e32 v5, 31, v1
	v_ashrrev_i32_e32 v1, 10, v1
	v_add_u32_e32 v1, v1, v5
	v_mul_i32_i24_e32 v1, 0x780, v1
	v_sub_u32_e32 v0, v0, v1
	s_movk_i32 s6, 0x8889
	v_mul_i32_i24_sdwa v1, sext(v0), s6 dst_sel:DWORD dst_unused:UNUSED_PAD src0_sel:WORD_0 src1_sel:DWORD
	v_add_u16_sdwa v1, v1, v0 dst_sel:DWORD dst_unused:UNUSED_PAD src0_sel:WORD_1 src1_sel:DWORD
	v_lshrrev_b16_e32 v5, 15, v1
	v_ashrrev_i16_e32 v1, 6, v1
	v_add_u16_e32 v1, v1, v5
	v_mul_lo_u16_e32 v5, 0x78, v1
	v_sub_u16_e32 v0, v0, v5
	v_mov_b32_e32 v5, 12
	v_lshrrev_b16_sdwa v5, v5, sext(v0) dst_sel:DWORD dst_unused:UNUSED_PAD src0_sel:DWORD src1_sel:BYTE_0
	v_and_b32_e32 v5, 7, v5
	v_add_u16_e32 v5, v0, v5
	v_and_b32_e32 v5, 0xf8, v5
	v_sub_u16_e32 v0, v0, v5
	v_bfe_i32 v1, v1, 0, 16
	v_bfe_i32 v0, v0, 0, 8
	v_lshl_add_u32 v0, v1, 3, v0
	v_ashrrev_i32_e32 v1, 31, v0
	v_lshlrev_b64 v[0:1], 14, v[0:1]
	v_lshl_add_u64 v[0:1], s[4:5], 0, v[0:1]
	v_lshl_add_u64 v[0:1], v[0:1], 0, v[140:141]
	global_load_dwordx4 v[48:51], v[0:1], off
	global_load_dwordx4 v[52:55], v[0:1], off offset:16
	global_load_dwordx4 v[56:59], v[0:1], off offset:32
	global_load_dwordx4 v[60:63], v[0:1], off offset:48
.LBB0_275:
	s_or_b64 exec, exec, s[34:35]
	v_add_u32_e32 v4, 4, v3
	v_mov_b64_e32 v[0:1], s[2:3]
	v_mad_i64_i32 v[0:1], s[10:11], v4, s56, v[0:1]
	s_mov_b64 s[10:11], 0x780
	s_nop 0
	v_cmp_gt_i64_e32 vcc, s[10:11], v[0:1]
	s_and_saveexec_b64 s[34:35], vcc
	s_cbranch_execz .LBB0_277
	v_ashrrev_i32_e32 v1, 31, v0
	v_lshrrev_b32_e32 v1, 29, v1
	v_add_u32_e32 v1, v0, v1
	v_ashrrev_i32_e32 v6, 3, v1
	v_and_b32_e32 v1, -8, v1
	v_sub_u32_e32 v0, v0, v1
	v_cmp_gt_i32_e32 vcc, 0, v0
	v_mov_b32_e32 v1, 0xf0
	v_mov_b32_e32 v5, 0xf1
	v_cndmask_b32_e32 v1, v1, v5, vcc
	v_mad_u64_u32 v[0:1], s[10:11], v0, v1, v[6:7]
	s_mov_b32 s6, 0x88888889
	v_mul_hi_i32 v1, v0, s6
	v_add_u32_e32 v1, v1, v0
	v_lshrrev_b32_e32 v5, 31, v1
	v_ashrrev_i32_e32 v1, 10, v1
	v_add_u32_e32 v1, v1, v5
	v_mul_i32_i24_e32 v1, 0x780, v1
	v_sub_u32_e32 v0, v0, v1
	s_movk_i32 s6, 0x8889
	v_mul_i32_i24_sdwa v1, sext(v0), s6 dst_sel:DWORD dst_unused:UNUSED_PAD src0_sel:WORD_0 src1_sel:DWORD
	v_add_u16_sdwa v1, v1, v0 dst_sel:DWORD dst_unused:UNUSED_PAD src0_sel:WORD_1 src1_sel:DWORD
	v_lshrrev_b16_e32 v5, 15, v1
	v_ashrrev_i16_e32 v1, 6, v1
	v_add_u16_e32 v1, v1, v5
	v_mul_lo_u16_e32 v5, 0x78, v1
	v_sub_u16_e32 v0, v0, v5
	v_mov_b32_e32 v5, 12
	v_lshrrev_b16_sdwa v5, v5, sext(v0) dst_sel:DWORD dst_unused:UNUSED_PAD src0_sel:DWORD src1_sel:BYTE_0
	v_and_b32_e32 v5, 7, v5
	v_add_u16_e32 v5, v0, v5
	v_and_b32_e32 v5, 0xf8, v5
	v_sub_u16_e32 v0, v0, v5
	v_bfe_i32 v1, v1, 0, 16
	v_bfe_i32 v0, v0, 0, 8
	v_lshl_add_u32 v0, v1, 3, v0
	v_ashrrev_i32_e32 v1, 31, v0
	v_lshlrev_b64 v[0:1], 14, v[0:1]
	v_lshl_add_u64 v[0:1], s[4:5], 0, v[0:1]
	v_lshl_add_u64 v[0:1], v[0:1], 0, v[140:141]
	global_load_dwordx4 v[64:67], v[0:1], off
	global_load_dwordx4 v[68:71], v[0:1], off offset:16
	global_load_dwordx4 v[72:75], v[0:1], off offset:32
	global_load_dwordx4 v[76:79], v[0:1], off offset:48
.LBB0_277:
	s_or_b64 exec, exec, s[34:35]
	v_add_u32_e32 v4, 6, v3
	v_mov_b64_e32 v[0:1], s[2:3]
	v_mad_i64_i32 v[0:1], s[10:11], v4, s56, v[0:1]
	s_mov_b64 s[10:11], 0x780
	s_nop 0
	v_cmp_gt_i64_e32 vcc, s[10:11], v[0:1]
	s_and_saveexec_b64 s[34:35], vcc
	s_cbranch_execz .LBB0_279
	v_ashrrev_i32_e32 v1, 31, v0
	v_lshrrev_b32_e32 v1, 29, v1
	v_add_u32_e32 v1, v0, v1
	v_ashrrev_i32_e32 v6, 3, v1
	v_and_b32_e32 v1, -8, v1
	v_sub_u32_e32 v0, v0, v1
	v_cmp_gt_i32_e32 vcc, 0, v0
	v_mov_b32_e32 v1, 0xf0
	v_mov_b32_e32 v5, 0xf1
	v_cndmask_b32_e32 v1, v1, v5, vcc
	v_mad_u64_u32 v[0:1], s[10:11], v0, v1, v[6:7]
	s_mov_b32 s6, 0x88888889
	v_mul_hi_i32 v1, v0, s6
	v_add_u32_e32 v1, v1, v0
	v_lshrrev_b32_e32 v5, 31, v1
	v_ashrrev_i32_e32 v1, 10, v1
	v_add_u32_e32 v1, v1, v5
	v_mul_i32_i24_e32 v1, 0x780, v1
	v_sub_u32_e32 v0, v0, v1
	s_movk_i32 s6, 0x8889
	v_mul_i32_i24_sdwa v1, sext(v0), s6 dst_sel:DWORD dst_unused:UNUSED_PAD src0_sel:WORD_0 src1_sel:DWORD
	v_add_u16_sdwa v1, v1, v0 dst_sel:DWORD dst_unused:UNUSED_PAD src0_sel:WORD_1 src1_sel:DWORD
	v_lshrrev_b16_e32 v5, 15, v1
	v_ashrrev_i16_e32 v1, 6, v1
	v_add_u16_e32 v1, v1, v5
	v_mul_lo_u16_e32 v5, 0x78, v1
	v_sub_u16_e32 v0, v0, v5
	v_mov_b32_e32 v5, 12
	v_lshrrev_b16_sdwa v5, v5, sext(v0) dst_sel:DWORD dst_unused:UNUSED_PAD src0_sel:DWORD src1_sel:BYTE_0
	v_and_b32_e32 v5, 7, v5
	v_add_u16_e32 v5, v0, v5
	v_and_b32_e32 v5, 0xf8, v5
	v_sub_u16_e32 v0, v0, v5
	v_bfe_i32 v1, v1, 0, 16
	v_bfe_i32 v0, v0, 0, 8
	v_lshl_add_u32 v0, v1, 3, v0
	v_ashrrev_i32_e32 v1, 31, v0
	v_lshlrev_b64 v[0:1], 14, v[0:1]
	v_lshl_add_u64 v[0:1], s[4:5], 0, v[0:1]
	v_lshl_add_u64 v[0:1], v[0:1], 0, v[140:141]
	global_load_dwordx4 v[80:83], v[0:1], off
	global_load_dwordx4 v[84:87], v[0:1], off offset:16
	global_load_dwordx4 v[88:91], v[0:1], off offset:32
	global_load_dwordx4 v[92:95], v[0:1], off offset:48
.LBB0_279:
	s_or_b64 exec, exec, s[34:35]
	v_add_u32_e32 v4, 8, v3
	v_mov_b64_e32 v[0:1], s[2:3]
	v_mad_i64_i32 v[0:1], s[10:11], v4, s56, v[0:1]
	s_mov_b64 s[10:11], 0x780
	s_nop 0
	v_cmp_gt_i64_e32 vcc, s[10:11], v[0:1]
	s_and_saveexec_b64 s[34:35], vcc
	s_cbranch_execz .LBB0_281
	v_ashrrev_i32_e32 v1, 31, v0
	v_lshrrev_b32_e32 v1, 29, v1
	v_add_u32_e32 v1, v0, v1
	v_ashrrev_i32_e32 v6, 3, v1
	v_and_b32_e32 v1, -8, v1
	v_sub_u32_e32 v0, v0, v1
	v_cmp_gt_i32_e32 vcc, 0, v0
	v_mov_b32_e32 v1, 0xf0
	v_mov_b32_e32 v5, 0xf1
	v_cndmask_b32_e32 v1, v1, v5, vcc
	v_mad_u64_u32 v[0:1], s[10:11], v0, v1, v[6:7]
	s_mov_b32 s6, 0x88888889
	v_mul_hi_i32 v1, v0, s6
	v_add_u32_e32 v1, v1, v0
	v_lshrrev_b32_e32 v5, 31, v1
	v_ashrrev_i32_e32 v1, 10, v1
	v_add_u32_e32 v1, v1, v5
	v_mul_i32_i24_e32 v1, 0x780, v1
	v_sub_u32_e32 v0, v0, v1
	s_movk_i32 s6, 0x8889
	v_mul_i32_i24_sdwa v1, sext(v0), s6 dst_sel:DWORD dst_unused:UNUSED_PAD src0_sel:WORD_0 src1_sel:DWORD
	v_add_u16_sdwa v1, v1, v0 dst_sel:DWORD dst_unused:UNUSED_PAD src0_sel:WORD_1 src1_sel:DWORD
	v_lshrrev_b16_e32 v5, 15, v1
	v_ashrrev_i16_e32 v1, 6, v1
	v_add_u16_e32 v1, v1, v5
	v_mul_lo_u16_e32 v5, 0x78, v1
	v_sub_u16_e32 v0, v0, v5
	v_mov_b32_e32 v5, 12
	v_lshrrev_b16_sdwa v5, v5, sext(v0) dst_sel:DWORD dst_unused:UNUSED_PAD src0_sel:DWORD src1_sel:BYTE_0
	v_and_b32_e32 v5, 7, v5
	v_add_u16_e32 v5, v0, v5
	v_and_b32_e32 v5, 0xf8, v5
	v_sub_u16_e32 v0, v0, v5
	v_bfe_i32 v1, v1, 0, 16
	v_bfe_i32 v0, v0, 0, 8
	v_lshl_add_u32 v0, v1, 3, v0
	v_ashrrev_i32_e32 v1, 31, v0
	v_lshlrev_b64 v[0:1], 14, v[0:1]
	v_lshl_add_u64 v[0:1], s[4:5], 0, v[0:1]
	v_lshl_add_u64 v[0:1], v[0:1], 0, v[140:141]
	global_load_dwordx4 v[96:99], v[0:1], off
	global_load_dwordx4 v[100:103], v[0:1], off offset:16
	global_load_dwordx4 v[104:107], v[0:1], off offset:32
	global_load_dwordx4 v[108:111], v[0:1], off offset:48
.LBB0_281:
	s_or_b64 exec, exec, s[34:35]
	v_add_u32_e32 v4, 10, v3
	v_mov_b64_e32 v[0:1], s[2:3]
	v_mad_i64_i32 v[0:1], s[10:11], v4, s56, v[0:1]
	s_mov_b64 s[10:11], 0x780
	s_nop 0
	v_cmp_gt_i64_e32 vcc, s[10:11], v[0:1]
	s_and_saveexec_b64 s[34:35], vcc
	s_cbranch_execz .LBB0_283
	v_ashrrev_i32_e32 v1, 31, v0
	v_lshrrev_b32_e32 v1, 29, v1
	v_add_u32_e32 v1, v0, v1
	v_ashrrev_i32_e32 v6, 3, v1
	v_and_b32_e32 v1, -8, v1
	v_sub_u32_e32 v0, v0, v1
	v_cmp_gt_i32_e32 vcc, 0, v0
	v_mov_b32_e32 v1, 0xf0
	v_mov_b32_e32 v5, 0xf1
	v_cndmask_b32_e32 v1, v1, v5, vcc
	v_mad_u64_u32 v[0:1], s[10:11], v0, v1, v[6:7]
	s_mov_b32 s6, 0x88888889
	v_mul_hi_i32 v1, v0, s6
	v_add_u32_e32 v1, v1, v0
	v_lshrrev_b32_e32 v5, 31, v1
	v_ashrrev_i32_e32 v1, 10, v1
	v_add_u32_e32 v1, v1, v5
	v_mul_i32_i24_e32 v1, 0x780, v1
	v_sub_u32_e32 v0, v0, v1
	s_movk_i32 s6, 0x8889
	v_mul_i32_i24_sdwa v1, sext(v0), s6 dst_sel:DWORD dst_unused:UNUSED_PAD src0_sel:WORD_0 src1_sel:DWORD
	v_add_u16_sdwa v1, v1, v0 dst_sel:DWORD dst_unused:UNUSED_PAD src0_sel:WORD_1 src1_sel:DWORD
	v_lshrrev_b16_e32 v5, 15, v1
	v_ashrrev_i16_e32 v1, 6, v1
	v_add_u16_e32 v1, v1, v5
	v_mul_lo_u16_e32 v5, 0x78, v1
	v_sub_u16_e32 v0, v0, v5
	v_mov_b32_e32 v5, 12
	v_lshrrev_b16_sdwa v5, v5, sext(v0) dst_sel:DWORD dst_unused:UNUSED_PAD src0_sel:DWORD src1_sel:BYTE_0
	v_and_b32_e32 v5, 7, v5
	v_add_u16_e32 v5, v0, v5
	v_and_b32_e32 v5, 0xf8, v5
	v_sub_u16_e32 v0, v0, v5
	v_bfe_i32 v1, v1, 0, 16
	v_bfe_i32 v0, v0, 0, 8
	v_lshl_add_u32 v0, v1, 3, v0
	v_ashrrev_i32_e32 v1, 31, v0
	v_lshlrev_b64 v[0:1], 14, v[0:1]
	v_lshl_add_u64 v[0:1], s[4:5], 0, v[0:1]
	v_lshl_add_u64 v[0:1], v[0:1], 0, v[140:141]
	global_load_dwordx4 v[112:115], v[0:1], off
	global_load_dwordx4 v[116:119], v[0:1], off offset:16
	global_load_dwordx4 v[120:123], v[0:1], off offset:32
	global_load_dwordx4 v[124:127], v[0:1], off offset:48
.LBB0_283:
	s_or_b64 exec, exec, s[34:35]
	v_add_u32_e32 v4, 12, v3
	v_mov_b64_e32 v[0:1], s[2:3]
	v_mad_i64_i32 v[0:1], s[10:11], v4, s56, v[0:1]
	s_mov_b64 s[10:11], 0x780
	s_nop 0
	v_cmp_gt_i64_e32 vcc, s[10:11], v[0:1]
	s_and_saveexec_b64 s[34:35], vcc
	s_cbranch_execz .LBB0_285
	v_ashrrev_i32_e32 v1, 31, v0
	v_lshrrev_b32_e32 v1, 29, v1
	v_add_u32_e32 v1, v0, v1
	v_ashrrev_i32_e32 v6, 3, v1
	v_and_b32_e32 v1, -8, v1
	v_sub_u32_e32 v0, v0, v1
	v_cmp_gt_i32_e32 vcc, 0, v0
	v_mov_b32_e32 v1, 0xf0
	v_mov_b32_e32 v5, 0xf1
	v_cndmask_b32_e32 v1, v1, v5, vcc
	v_mad_u64_u32 v[0:1], s[10:11], v0, v1, v[6:7]
	s_mov_b32 s6, 0x88888889
	v_mul_hi_i32 v1, v0, s6
	v_add_u32_e32 v1, v1, v0
	v_lshrrev_b32_e32 v5, 31, v1
	v_ashrrev_i32_e32 v1, 10, v1
	v_add_u32_e32 v1, v1, v5
	v_mul_i32_i24_e32 v1, 0x780, v1
	v_sub_u32_e32 v0, v0, v1
	s_movk_i32 s6, 0x8889
	v_mul_i32_i24_sdwa v1, sext(v0), s6 dst_sel:DWORD dst_unused:UNUSED_PAD src0_sel:WORD_0 src1_sel:DWORD
	v_add_u16_sdwa v1, v1, v0 dst_sel:DWORD dst_unused:UNUSED_PAD src0_sel:WORD_1 src1_sel:DWORD
	v_lshrrev_b16_e32 v5, 15, v1
	v_ashrrev_i16_e32 v1, 6, v1
	v_add_u16_e32 v1, v1, v5
	v_mul_lo_u16_e32 v5, 0x78, v1
	v_sub_u16_e32 v0, v0, v5
	v_mov_b32_e32 v5, 12
	v_lshrrev_b16_sdwa v5, v5, sext(v0) dst_sel:DWORD dst_unused:UNUSED_PAD src0_sel:DWORD src1_sel:BYTE_0
	v_and_b32_e32 v5, 7, v5
	v_add_u16_e32 v5, v0, v5
	v_and_b32_e32 v5, 0xf8, v5
	v_sub_u16_e32 v0, v0, v5
	v_bfe_i32 v1, v1, 0, 16
	v_bfe_i32 v0, v0, 0, 8
	v_lshl_add_u32 v0, v1, 3, v0
	v_ashrrev_i32_e32 v1, 31, v0
	v_lshlrev_b64 v[0:1], 14, v[0:1]
	v_lshl_add_u64 v[0:1], s[4:5], 0, v[0:1]
	v_lshl_add_u64 v[0:1], v[0:1], 0, v[140:141]
	global_load_dwordx4 v[146:149], v[0:1], off
	global_load_dwordx4 v[150:153], v[0:1], off offset:16
	global_load_dwordx4 v[154:157], v[0:1], off offset:32
	global_load_dwordx4 v[158:161], v[0:1], off offset:48
.LBB0_285:
	s_or_b64 exec, exec, s[34:35]
	v_add_u32_e32 v3, 14, v3
	v_mov_b64_e32 v[0:1], s[2:3]
	v_mad_i64_i32 v[0:1], s[10:11], v3, s56, v[0:1]
	s_mov_b64 s[10:11], 0x780
	s_nop 0
	v_cmp_gt_i64_e32 vcc, s[10:11], v[0:1]
	s_and_saveexec_b64 s[34:35], vcc
	s_cbranch_execz .LBB0_287
	v_ashrrev_i32_e32 v1, 31, v0
	v_lshrrev_b32_e32 v1, 29, v1
	v_add_u32_e32 v1, v0, v1
	v_ashrrev_i32_e32 v4, 3, v1
	v_and_b32_e32 v1, -8, v1
	v_sub_u32_e32 v0, v0, v1
	v_cmp_gt_i32_e32 vcc, 0, v0
	v_mov_b32_e32 v1, 0xf0
	v_mov_b32_e32 v5, 0xf1
	v_cndmask_b32_e32 v1, v1, v5, vcc
	v_mad_u64_u32 v[0:1], s[10:11], v0, v1, v[4:5]
	s_mov_b32 s6, 0x88888889
	v_mul_hi_i32 v1, v0, s6
	v_add_u32_e32 v1, v1, v0
	v_lshrrev_b32_e32 v4, 31, v1
	v_ashrrev_i32_e32 v1, 10, v1
	v_add_u32_e32 v1, v1, v4
	v_mul_i32_i24_e32 v1, 0x780, v1
	v_sub_u32_e32 v0, v0, v1
	s_movk_i32 s6, 0x8889
	v_mul_i32_i24_sdwa v1, sext(v0), s6 dst_sel:DWORD dst_unused:UNUSED_PAD src0_sel:WORD_0 src1_sel:DWORD
	v_add_u16_sdwa v1, v1, v0 dst_sel:DWORD dst_unused:UNUSED_PAD src0_sel:WORD_1 src1_sel:DWORD
	v_lshrrev_b16_e32 v4, 15, v1
	v_ashrrev_i16_e32 v1, 6, v1
	v_add_u16_e32 v1, v1, v4
	v_mul_lo_u16_e32 v4, 0x78, v1
	v_sub_u16_e32 v0, v0, v4
	v_mov_b32_e32 v4, 12
	v_lshrrev_b16_sdwa v4, v4, sext(v0) dst_sel:DWORD dst_unused:UNUSED_PAD src0_sel:DWORD src1_sel:BYTE_0
	v_and_b32_e32 v4, 7, v4
	v_add_u16_e32 v4, v0, v4
	v_and_b32_e32 v4, 0xf8, v4
	v_sub_u16_e32 v0, v0, v4
	v_bfe_i32 v1, v1, 0, 16
	v_bfe_i32 v0, v0, 0, 8
	v_lshl_add_u32 v0, v1, 3, v0
	v_ashrrev_i32_e32 v1, 31, v0
	v_lshlrev_b64 v[0:1], 14, v[0:1]
	v_lshl_add_u64 v[0:1], s[4:5], 0, v[0:1]
	v_lshl_add_u64 v[0:1], v[0:1], 0, v[140:141]
	global_load_dwordx4 v[162:165], v[0:1], off
	global_load_dwordx4 v[166:169], v[0:1], off offset:16
	global_load_dwordx4 v[170:173], v[0:1], off offset:32
	global_load_dwordx4 v[174:177], v[0:1], off offset:48
.LBB0_287:
	s_or_b64 exec, exec, s[34:35]
	s_waitcnt vmcnt(0)
	v_add_u32_e32 v3, -14, v3
	v_mov_b32_e32 v4, v3
	v_mov_b64_e32 v[0:1], s[2:3]
	v_mad_i64_i32 v[0:1], s[10:11], v4, s56, v[0:1]
	s_mov_b64 s[10:11], 0x780
	s_nop 0
	v_cmp_gt_i64_e32 vcc, s[10:11], v[0:1]
	s_and_saveexec_b64 s[34:35], vcc
	s_cbranch_execz my_rs1_0
	v_pk_add_f32 v[0:1], v[34:35], v[38:39]
	v_pk_add_f32 v[32:33], v[32:33], v[36:37]
	v_pk_add_f32 v[34:35], v[42:43], v[46:47]
	v_pk_add_f32 v[36:37], v[40:41], v[44:45]
	v_pk_add_f32 v[0:1], v[0:1], v[34:35]
	v_pk_add_f32 v[32:33], v[32:33], v[36:37]
	s_nop 0
	v_pk_mov_b32 v[34:35], v[32:33], v[0:1] op_sel:[1,0]
	v_mov_b32_e32 v33, v1
	v_pk_add_f32 v[0:1], v[34:35], v[32:33]
	s_nop 0
	v_add_f32_e32 v0, v0, v1
	v_fmamk_f32 v0, v0, 0x3a800000, v187
	v_mul_f32_e32 v1, 0x4b800000, v0
	v_cmp_gt_f32_e32 vcc, s78, v0
	s_nop 1
	v_cndmask_b32_e32 v0, v0, v1, vcc
	v_rsq_f32_e32 v0, v0
	s_nop 0
	v_mul_f32_e32 v1, 0x45800000, v0
	v_cndmask_b32_e32 v0, v0, v1, vcc
	v_lshl_add_u32 v1, v3, 10, v2
	ds_write_b32 v1, v0
my_rs1_0:
	s_or_b64 exec, exec, s[34:35]
	v_add_u32_e32 v4, 2, v3
	v_mov_b64_e32 v[0:1], s[2:3]
	v_mad_i64_i32 v[0:1], s[10:11], v4, s56, v[0:1]
	s_mov_b64 s[10:11], 0x780
	s_nop 0
	v_cmp_gt_i64_e32 vcc, s[10:11], v[0:1]
	s_and_saveexec_b64 s[34:35], vcc
	s_cbranch_execz my_rs1_1
	v_pk_add_f32 v[0:1], v[50:51], v[54:55]
	v_pk_add_f32 v[6:7], v[48:49], v[52:53]
	v_pk_add_f32 v[48:49], v[58:59], v[62:63]
	v_pk_add_f32 v[50:51], v[56:57], v[60:61]
	v_pk_add_f32 v[0:1], v[0:1], v[48:49]
	v_pk_add_f32 v[6:7], v[6:7], v[50:51]
	s_nop 0
	v_pk_mov_b32 v[48:49], v[6:7], v[0:1] op_sel:[1,0]
	v_mov_b32_e32 v7, v1
	v_pk_add_f32 v[0:1], v[48:49], v[6:7]
	s_nop 0
	v_add_f32_e32 v0, v0, v1
	v_fmamk_f32 v0, v0, 0x3a800000, v187
	v_mul_f32_e32 v1, 0x4b800000, v0
	v_cmp_gt_f32_e32 vcc, s78, v0
	s_nop 1
	v_cndmask_b32_e32 v0, v0, v1, vcc
	v_rsq_f32_e32 v0, v0
	s_nop 0
	v_mul_f32_e32 v1, 0x45800000, v0
	v_cndmask_b32_e32 v0, v0, v1, vcc
	v_lshl_add_u32 v1, v4, 10, v2
	ds_write_b32 v1, v0
my_rs1_1:
	s_or_b64 exec, exec, s[34:35]
	v_add_u32_e32 v4, 4, v3
	v_mov_b64_e32 v[0:1], s[2:3]
	v_mad_i64_i32 v[0:1], s[10:11], v4, s56, v[0:1]
	s_mov_b64 s[10:11], 0x780
	s_nop 0
	v_cmp_gt_i64_e32 vcc, s[10:11], v[0:1]
	s_and_saveexec_b64 s[34:35], vcc
	s_cbranch_execz my_rs1_2
	v_pk_add_f32 v[0:1], v[66:67], v[70:71]
	v_pk_add_f32 v[6:7], v[64:65], v[68:69]
	v_pk_add_f32 v[64:65], v[74:75], v[78:79]
	v_pk_add_f32 v[66:67], v[72:73], v[76:77]
	v_pk_add_f32 v[0:1], v[0:1], v[64:65]
	v_pk_add_f32 v[6:7], v[6:7], v[66:67]
	s_nop 0
	v_pk_mov_b32 v[64:65], v[6:7], v[0:1] op_sel:[1,0]
	v_mov_b32_e32 v7, v1
	v_pk_add_f32 v[0:1], v[64:65], v[6:7]
	s_nop 0
	v_add_f32_e32 v0, v0, v1
	v_fmamk_f32 v0, v0, 0x3a800000, v187
	v_mul_f32_e32 v1, 0x4b800000, v0
	v_cmp_gt_f32_e32 vcc, s78, v0
	s_nop 1
	v_cndmask_b32_e32 v0, v0, v1, vcc
	v_rsq_f32_e32 v0, v0
	s_nop 0
	v_mul_f32_e32 v1, 0x45800000, v0
	v_cndmask_b32_e32 v0, v0, v1, vcc
	v_lshl_add_u32 v1, v4, 10, v2
	ds_write_b32 v1, v0
my_rs1_2:
	s_or_b64 exec, exec, s[34:35]
	v_add_u32_e32 v4, 6, v3
	v_mov_b64_e32 v[0:1], s[2:3]
	v_mad_i64_i32 v[0:1], s[10:11], v4, s56, v[0:1]
	s_mov_b64 s[10:11], 0x780
	s_nop 0
	v_cmp_gt_i64_e32 vcc, s[10:11], v[0:1]
	s_and_saveexec_b64 s[34:35], vcc
	s_cbranch_execz my_rs1_3
	v_pk_add_f32 v[0:1], v[82:83], v[86:87]
	v_pk_add_f32 v[6:7], v[80:81], v[84:85]
	v_pk_add_f32 v[80:81], v[90:91], v[94:95]
	v_pk_add_f32 v[82:83], v[88:89], v[92:93]
	v_pk_add_f32 v[0:1], v[0:1], v[80:81]
	v_pk_add_f32 v[6:7], v[6:7], v[82:83]
	s_nop 0
	v_pk_mov_b32 v[80:81], v[6:7], v[0:1] op_sel:[1,0]
	v_mov_b32_e32 v7, v1
	v_pk_add_f32 v[0:1], v[80:81], v[6:7]
	s_nop 0
	v_add_f32_e32 v0, v0, v1
	v_fmamk_f32 v0, v0, 0x3a800000, v187
	v_mul_f32_e32 v1, 0x4b800000, v0
	v_cmp_gt_f32_e32 vcc, s78, v0
	s_nop 1
	v_cndmask_b32_e32 v0, v0, v1, vcc
	v_rsq_f32_e32 v0, v0
	s_nop 0
	v_mul_f32_e32 v1, 0x45800000, v0
	v_cndmask_b32_e32 v0, v0, v1, vcc
	v_lshl_add_u32 v1, v4, 10, v2
	ds_write_b32 v1, v0
my_rs1_3:
	s_or_b64 exec, exec, s[34:35]
	v_add_u32_e32 v4, 8, v3
	v_mov_b64_e32 v[0:1], s[2:3]
	v_mad_i64_i32 v[0:1], s[10:11], v4, s56, v[0:1]
	s_mov_b64 s[10:11], 0x780
	s_nop 0
	v_cmp_gt_i64_e32 vcc, s[10:11], v[0:1]
	s_and_saveexec_b64 s[34:35], vcc
	s_cbranch_execz my_rs1_4
	v_pk_add_f32 v[0:1], v[98:99], v[102:103]
	v_pk_add_f32 v[6:7], v[96:97], v[100:101]
	v_pk_add_f32 v[96:97], v[106:107], v[110:111]
	v_pk_add_f32 v[98:99], v[104:105], v[108:109]
	v_pk_add_f32 v[0:1], v[0:1], v[96:97]
	v_pk_add_f32 v[6:7], v[6:7], v[98:99]
	s_nop 0
	v_pk_mov_b32 v[96:97], v[6:7], v[0:1] op_sel:[1,0]
	v_mov_b32_e32 v7, v1
	v_pk_add_f32 v[0:1], v[96:97], v[6:7]
	s_nop 0
	v_add_f32_e32 v0, v0, v1
	v_fmamk_f32 v0, v0, 0x3a800000, v187
	v_mul_f32_e32 v1, 0x4b800000, v0
	v_cmp_gt_f32_e32 vcc, s78, v0
	s_nop 1
	v_cndmask_b32_e32 v0, v0, v1, vcc
	v_rsq_f32_e32 v0, v0
	s_nop 0
	v_mul_f32_e32 v1, 0x45800000, v0
	v_cndmask_b32_e32 v0, v0, v1, vcc
	v_lshl_add_u32 v1, v4, 10, v2
	ds_write_b32 v1, v0
my_rs1_4:
	s_or_b64 exec, exec, s[34:35]
	v_add_u32_e32 v4, 10, v3
	v_mov_b64_e32 v[0:1], s[2:3]
	v_mad_i64_i32 v[0:1], s[10:11], v4, s56, v[0:1]
	s_mov_b64 s[10:11], 0x780
	s_nop 0
	v_cmp_gt_i64_e32 vcc, s[10:11], v[0:1]
	s_and_saveexec_b64 s[34:35], vcc
	s_cbranch_execz my_rs1_5
	v_pk_add_f32 v[0:1], v[114:115], v[118:119]
	v_pk_add_f32 v[6:7], v[112:113], v[116:117]
	v_pk_add_f32 v[112:113], v[122:123], v[126:127]
	v_pk_add_f32 v[114:115], v[120:121], v[124:125]
	v_pk_add_f32 v[0:1], v[0:1], v[112:113]
	v_pk_add_f32 v[6:7], v[6:7], v[114:115]
	s_nop 0
	v_pk_mov_b32 v[112:113], v[6:7], v[0:1] op_sel:[1,0]
	v_mov_b32_e32 v7, v1
	v_pk_add_f32 v[0:1], v[112:113], v[6:7]
	s_nop 0
	v_add_f32_e32 v0, v0, v1
	v_fmamk_f32 v0, v0, 0x3a800000, v187
	v_mul_f32_e32 v1, 0x4b800000, v0
	v_cmp_gt_f32_e32 vcc, s78, v0
	s_nop 1
	v_cndmask_b32_e32 v0, v0, v1, vcc
	v_rsq_f32_e32 v0, v0
	s_nop 0
	v_mul_f32_e32 v1, 0x45800000, v0
	v_cndmask_b32_e32 v0, v0, v1, vcc
	v_lshl_add_u32 v1, v4, 10, v2
	ds_write_b32 v1, v0
my_rs1_5:
	s_or_b64 exec, exec, s[34:35]
	v_add_u32_e32 v4, 12, v3
	v_mov_b64_e32 v[0:1], s[2:3]
	v_mad_i64_i32 v[0:1], s[10:11], v4, s56, v[0:1]
	s_mov_b64 s[10:11], 0x780
	s_nop 0
	v_cmp_gt_i64_e32 vcc, s[10:11], v[0:1]
	s_and_saveexec_b64 s[34:35], vcc
	s_cbranch_execz my_rs1_6
	v_pk_add_f32 v[0:1], v[148:149], v[152:153]
	v_pk_add_f32 v[6:7], v[146:147], v[150:151]
	v_pk_add_f32 v[146:147], v[156:157], v[160:161]
	v_pk_add_f32 v[148:149], v[154:155], v[158:159]
	v_pk_add_f32 v[0:1], v[0:1], v[146:147]
	v_pk_add_f32 v[6:7], v[6:7], v[148:149]
	s_nop 0
	v_pk_mov_b32 v[146:147], v[6:7], v[0:1] op_sel:[1,0]
	v_mov_b32_e32 v7, v1
	v_pk_add_f32 v[0:1], v[146:147], v[6:7]
	s_nop 0
	v_add_f32_e32 v0, v0, v1
	v_fmamk_f32 v0, v0, 0x3a800000, v187
	v_mul_f32_e32 v1, 0x4b800000, v0
	v_cmp_gt_f32_e32 vcc, s78, v0
	s_nop 1
	v_cndmask_b32_e32 v0, v0, v1, vcc
	v_rsq_f32_e32 v0, v0
	s_nop 0
	v_mul_f32_e32 v1, 0x45800000, v0
	v_cndmask_b32_e32 v0, v0, v1, vcc
	v_lshl_add_u32 v1, v4, 10, v2
	ds_write_b32 v1, v0
my_rs1_6:
	s_or_b64 exec, exec, s[34:35]
	v_add_u32_e32 v3, 14, v3
	v_mov_b64_e32 v[0:1], s[2:3]
	v_mad_i64_i32 v[0:1], s[10:11], v3, s56, v[0:1]
	s_mov_b64 s[10:11], 0x780
	s_nop 0
	v_cmp_gt_i64_e32 vcc, s[10:11], v[0:1]
	s_and_saveexec_b64 s[34:35], vcc
	s_cbranch_execz my_rs1_7
	v_pk_add_f32 v[0:1], v[164:165], v[168:169]
	v_pk_add_f32 v[162:163], v[162:163], v[166:167]
	v_pk_add_f32 v[164:165], v[172:173], v[176:177]
	v_pk_add_f32 v[166:167], v[170:171], v[174:175]
	v_pk_add_f32 v[0:1], v[0:1], v[164:165]
	v_pk_add_f32 v[162:163], v[162:163], v[166:167]
	s_nop 0
	v_pk_mov_b32 v[164:165], v[162:163], v[0:1] op_sel:[1,0]
	v_mov_b32_e32 v163, v1
	v_pk_add_f32 v[0:1], v[164:165], v[162:163]
	s_nop 0
	v_add_f32_e32 v0, v0, v1
	v_fmamk_f32 v0, v0, 0x3a800000, v187
	v_mul_f32_e32 v1, 0x4b800000, v0
	v_cmp_gt_f32_e32 vcc, s78, v0
	s_nop 1
	v_cndmask_b32_e32 v0, v0, v1, vcc
	v_rsq_f32_e32 v0, v0
	s_nop 0
	v_mul_f32_e32 v1, 0x45800000, v0
	v_cndmask_b32_e32 v0, v0, v1, vcc
	v_lshl_add_u32 v1, v3, 10, v2
	ds_write_b32 v1, v0
my_rs1_7:
	s_or_b64 exec, exec, s[34:35]
	v_readlane_b32 s4, v252, 19
	v_readlane_b32 s5, v252, 20
	s_andn2_b64 vcc, exec, s[4:5]
	s_waitcnt vmcnt(0) lgkmcnt(0)
	s_barrier
	s_cbranch_vccnz .LBB0_301
	v_ashrrev_i32_e32 v1, 31, v8
	v_lshrrev_b32_e32 v1, 26, v1
	v_add_u32_e32 v1, v8, v1
	v_ashrrev_i32_e32 v9, 6, v1
	v_bfe_i32 v1, v8, 27, 1
	v_lshlrev_b32_e32 v0, 4, v8
	v_lshrrev_b32_e32 v1, 22, v1
	v_add_u32_e32 v1, v0, v1
	v_and_b32_e32 v1, 0xfffffc00, v1
	v_sub_u32_e32 v1, v0, v1
	v_lshrrev_b32_e32 v2, 4, v1
	v_bitop3_b32 v2, v2, v1, 32 bitop3:0x6c
	v_ashrrev_i32_e32 v1, 31, v1
	v_lshrrev_b32_e32 v1, 26, v1
	v_add_u32_e32 v1, v2, v1
	v_ashrrev_i32_e32 v10, 6, v1
	v_lshlrev_b32_e32 v3, 3, v9
	v_mul_i32_i24_e32 v4, 64, v10
	v_and_b32_e32 v3, -16, v3
	v_sub_u32_e32 v2, v2, v4
	v_mov_b32_e32 v6, 1
	v_add_u32_e32 v1, v10, v3
	v_lshlrev_b32_e32 v3, 5, v9
	v_ashrrev_i16_sdwa v2, v6, sext(v2) dst_sel:DWORD dst_unused:UNUSED_PAD src0_sel:DWORD src1_sel:BYTE_0
	v_and_b32_e32 v3, 32, v3
	v_bfe_i32 v11, v2, 0, 16
	v_and_b32_e32 v5, 3, v10
	s_mov_b32 s4, 0x1fffe0
	v_add_lshl_u32 v3, v3, v11, 1
	v_add_u32_e32 v0, 0x2000, v0
	v_lshlrev_b32_e32 v2, 1, v1
	v_lshrrev_b32_e32 v4, 2, v1
	v_and_or_b32 v5, v1, s4, v5
	v_lshl_add_u32 v128, v1, 11, v3
	v_ashrrev_i32_e32 v1, 31, v0
	v_lshrrev_b32_e32 v1, 22, v1
	v_add_u32_e32 v1, v0, v1
	v_ashrrev_i32_e32 v12, 10, v1
	v_mul_i32_i24_e32 v1, 0x400, v12
	v_sub_u32_e32 v0, v0, v1
	v_and_b32_e32 v2, 24, v2
	v_and_b32_e32 v4, 4, v4
	v_lshrrev_b32_e32 v1, 4, v0
	v_or3_b32 v2, v5, v4, v2
	v_bitop3_b32 v0, v1, v0, 32 bitop3:0x6c
	v_lshl_add_u32 v140, v2, 11, v3
	v_ashrrev_i32_e32 v2, 31, v0
	s_add_u32 s33, s30, 0x12290000
	v_lshrrev_b32_e32 v2, 26, v2
	s_addc_u32 s41, s31, 0
	v_lshlrev_b32_e32 v1, 3, v12
	v_add_u32_e32 v2, v0, v2
	s_add_u32 s54, s28, 0x1080000
	v_and_b32_e32 v1, -16, v1
	v_ashrrev_i32_e32 v13, 6, v2
	s_addc_u32 s55, s29, 0
	v_add_u32_e32 v1, v13, v1
	v_and_b32_e32 v2, 0xc0, v2
	v_and_b32_e32 v4, 3, v13
	s_ashr_i32 s10, s9, 6
	s_ashr_i32 s6, s9, 8
	v_sub_u32_e32 v0, v0, v2
	v_and_or_b32 v4, v1, s4, v4
	s_lshl_b32 s57, s10, 10
	v_readlane_b32 s4, v253, 47
	v_ashrrev_i16_sdwa v0, v6, sext(v0) dst_sel:DWORD dst_unused:UNUSED_PAD src0_sel:DWORD src1_sel:BYTE_0
	v_readlane_b32 s5, v253, 48
	s_add_u32 s48, s54, s4
	v_lshlrev_b32_e32 v3, 5, v12
	v_bfe_i32 v14, v0, 0, 16
	v_lshlrev_b32_e32 v0, 1, v1
	v_lshrrev_b32_e32 v2, 2, v1
	s_addc_u32 s49, s55, s5
	s_add_i32 s58, s57, 0
	v_and_b32_e32 v3, 32, v3
	v_and_b32_e32 v0, 24, v0
	v_and_b32_e32 v2, 4, v2
	s_add_i32 m0, s58, 0x10000
	v_or3_b32 v0, v4, v2, v0
	v_add_lshl_u32 v2, v3, v14, 1
	global_load_lds_dwordx4 v140, s[48:49]
	s_add_i32 m0, s58, 0x12000
	v_readlane_b32 s4, v253, 62
	v_lshl_add_u32 v132, v0, 11, v2
	v_readlane_b32 s5, v253, 63
	s_add_u32 s4, s33, s4
	global_load_lds_dwordx4 v132, s[48:49]
	s_addc_u32 s5, s41, s5
	s_mov_b32 m0, s58
	s_add_i32 s59, s58, 0x2000
	v_lshl_add_u32 v130, v1, 11, v2
	global_load_lds_dwordx4 v128, s[4:5]
	s_mov_b32 m0, s59
	s_add_u32 s28, s48, 0x40000
	global_load_lds_dwordx4 v130, s[4:5]
	s_addc_u32 s29, s49, 0
	s_add_i32 m0, s58, 0x14000
	v_mov_b32_e32 v133, v141
	global_load_lds_dwordx4 v140, s[28:29]
	s_add_i32 m0, s58, 0x16000
	v_mov_b32_e32 v129, v141
	global_load_lds_dwordx4 v132, s[28:29]
	s_add_u32 s28, s4, 0x40000
	s_addc_u32 s29, s5, 0
	s_add_i32 s68, s58, 0x4000
	s_mov_b32 m0, s68
	s_add_i32 s69, s58, 0x6000
	global_load_lds_dwordx4 v128, s[28:29]
	s_mov_b32 m0, s69
	v_mov_b32_e32 v131, v141
	global_load_lds_dwordx4 v130, s[28:29]
	v_lshl_add_u64 v[6:7], s[48:49], 0, v[140:141]
	v_lshl_add_u64 v[4:5], s[48:49], 0, v[132:133]
	v_lshl_add_u64 v[2:3], s[4:5], 0, v[128:129]
	s_cmp_lg_u32 s6, 1
	v_lshl_add_u64 v[0:1], s[4:5], 0, v[130:131]
	s_cbranch_scc1 .LBB0_290
	s_barrier

.LBB0_359:
	s_and_b64 vcc, exec, s[26:27]
	s_cbranch_vccz .LBB0_444
	s_cmp_gt_i32 s60, 0
	s_mov_b64 s[26:27], -1
	s_cbranch_scc0 .LBB0_394
	s_cmp_lt_i32 s60, 2
	s_cbranch_scc0 .LBB0_393
	s_mov_b64 s[26:27], s[0:1]
	s_mov_b64 s[30:31], s[0:1]
	s_mov_b64 s[38:39], s[0:1]
	s_mov_b64 s[10:11], s[0:1]
	s_load_dwordx2 s[10:11], s[10:11], 0xf8
	v_mov_b32_e32 v8, v186
	s_waitcnt lgkmcnt(0)
	v_mov_b64_e32 v[0:1], s[2:3]
	v_ashrrev_i32_e32 v3, 8, v8
	s_add_u32 s28, s10, 0x1df14000
	s_addc_u32 s29, s11, 0
	v_mad_i64_i32 v[0:1], s[10:11], v3, s56, v[0:1]
	v_and_b32_e32 v4, 0xff, v8
	v_readlane_b32 s6, v254, 59
	s_mov_b64 s[10:11], 0xb00
	v_readfirstlane_b32 s9, v8
	v_lshl_add_u32 v2, v4, 2, s6
	v_cmp_gt_i64_e32 vcc, s[10:11], v[0:1]
	v_lshlrev_b32_e32 v140, 6, v4
	s_and_saveexec_b64 s[34:35], vcc
	s_cbranch_execz .LBB0_364
	v_ashrrev_i32_e32 v1, 31, v0
	v_lshrrev_b32_e32 v1, 29, v1
	v_add_u32_e32 v1, v0, v1
	v_ashrrev_i32_e32 v4, 3, v1
	v_and_b32_e32 v1, -8, v1
	v_sub_u32_e32 v0, v0, v1
	v_cmp_gt_i32_e32 vcc, 0, v0
	v_mov_b32_e32 v1, 0x161
	v_mov_b32_e32 v5, 0x160
	v_cndmask_b32_e32 v1, v5, v1, vcc
	v_mad_u64_u32 v[0:1], s[10:11], v0, v1, v[4:5]
	s_mov_b32 s6, 0x2e8ba2e9
	v_mul_hi_i32 v1, v0, s6
	v_lshrrev_b32_e32 v4, 31, v1
	v_ashrrev_i32_e32 v1, 9, v1
	v_add_u32_e32 v1, v1, v4
	v_mul_i32_i24_e32 v1, 0xb00, v1
	v_sub_u32_e32 v0, v0, v1
	s_movk_i32 s6, 0xba3
	v_mul_i32_i24_sdwa v1, sext(v0), s6 dst_sel:DWORD dst_unused:UNUSED_PAD src0_sel:WORD_0 src1_sel:DWORD
	v_lshrrev_b32_e32 v4, 31, v1
	v_ashrrev_i32_e32 v1, 19, v1
	v_add_u16_e32 v1, v1, v4
	v_mul_lo_u16_e32 v4, 0xb0, v1
	v_sub_u16_e32 v0, v0, v4
	v_ashrrev_i16_e32 v4, 15, v0
	v_lshrrev_b16_e32 v4, 13, v4
	v_add_u16_e32 v4, v0, v4
	v_and_b32_e32 v4, -8, v4
	v_sub_u16_e32 v0, v0, v4
	v_bfe_i32 v1, v1, 0, 16
	v_bfe_i32 v0, v0, 0, 16
	v_lshl_add_u32 v0, v1, 3, v0
	v_ashrrev_i32_e32 v1, 31, v0
	v_lshlrev_b64 v[0:1], 14, v[0:1]
	v_lshl_add_u64 v[0:1], s[28:29], 0, v[0:1]
	v_lshl_add_u64 v[0:1], v[0:1], 0, v[140:141]
	global_load_dwordx4 v[32:35], v[0:1], off
	global_load_dwordx4 v[36:39], v[0:1], off offset:16
	global_load_dwordx4 v[40:43], v[0:1], off offset:32
	global_load_dwordx4 v[44:47], v[0:1], off offset:48
.LBB0_364:
	s_or_b64 exec, exec, s[34:35]
	s_load_dwordx2 s[34:35], s[26:27], 0xf8
	s_nop 0
	s_load_dwordx2 s[26:27], s[30:31], 0xf8
	s_nop 0
	s_load_dwordx2 s[30:31], s[38:39], 0xf8
	v_add_u32_e32 v4, 2, v3
	v_mov_b64_e32 v[0:1], s[2:3]
	v_mad_i64_i32 v[0:1], s[10:11], v4, s56, v[0:1]
	s_mov_b64 s[10:11], 0xb00
	s_nop 0
	v_cmp_gt_i64_e32 vcc, s[10:11], v[0:1]
	s_and_saveexec_b64 s[38:39], vcc
	s_cbranch_execz .LBB0_366
	v_ashrrev_i32_e32 v1, 31, v0
	v_lshrrev_b32_e32 v1, 29, v1
	v_add_u32_e32 v1, v0, v1
	v_ashrrev_i32_e32 v6, 3, v1
	v_and_b32_e32 v1, -8, v1
	v_sub_u32_e32 v0, v0, v1
	v_cmp_gt_i32_e32 vcc, 0, v0
	v_mov_b32_e32 v1, 0x161
	v_mov_b32_e32 v5, 0x160
	v_cndmask_b32_e32 v1, v5, v1, vcc
	v_mad_u64_u32 v[0:1], s[10:11], v0, v1, v[6:7]
	s_mov_b32 s6, 0x2e8ba2e9
	v_mul_hi_i32 v1, v0, s6
	v_lshrrev_b32_e32 v5, 31, v1
	v_ashrrev_i32_e32 v1, 9, v1
	v_add_u32_e32 v1, v1, v5
	v_mul_i32_i24_e32 v1, 0xb00, v1
	v_sub_u32_e32 v0, v0, v1
	s_movk_i32 s6, 0xba3
	v_mul_i32_i24_sdwa v1, sext(v0), s6 dst_sel:DWORD dst_unused:UNUSED_PAD src0_sel:WORD_0 src1_sel:DWORD
	v_lshrrev_b32_e32 v5, 31, v1
	v_ashrrev_i32_e32 v1, 19, v1
	v_add_u16_e32 v1, v1, v5
	v_mul_lo_u16_e32 v5, 0xb0, v1
	v_sub_u16_e32 v0, v0, v5
	v_ashrrev_i16_e32 v5, 15, v0
	v_lshrrev_b16_e32 v5, 13, v5
	v_add_u16_e32 v5, v0, v5
	v_and_b32_e32 v5, -8, v5
	v_sub_u16_e32 v0, v0, v5
	v_bfe_i32 v1, v1, 0, 16
	v_bfe_i32 v0, v0, 0, 16
	v_lshl_add_u32 v0, v1, 3, v0
	v_ashrrev_i32_e32 v1, 31, v0
	v_lshlrev_b64 v[0:1], 14, v[0:1]
	v_lshl_add_u64 v[0:1], s[28:29], 0, v[0:1]
	v_lshl_add_u64 v[0:1], v[0:1], 0, v[140:141]
	global_load_dwordx4 v[48:51], v[0:1], off
	global_load_dwordx4 v[52:55], v[0:1], off offset:16
	global_load_dwordx4 v[56:59], v[0:1], off offset:32
	global_load_dwordx4 v[60:63], v[0:1], off offset:48
.LBB0_366:
	s_or_b64 exec, exec, s[38:39]
	v_add_u32_e32 v4, 4, v3
	v_mov_b64_e32 v[0:1], s[2:3]
	v_mad_i64_i32 v[0:1], s[10:11], v4, s56, v[0:1]
	s_mov_b64 s[10:11], 0xb00
	s_nop 0
	v_cmp_gt_i64_e32 vcc, s[10:11], v[0:1]
	s_and_saveexec_b64 s[38:39], vcc
	s_cbranch_execz .LBB0_368
	v_ashrrev_i32_e32 v1, 31, v0
	v_lshrrev_b32_e32 v1, 29, v1
	v_add_u32_e32 v1, v0, v1
	v_ashrrev_i32_e32 v6, 3, v1
	v_and_b32_e32 v1, -8, v1
	v_sub_u32_e32 v0, v0, v1
	v_cmp_gt_i32_e32 vcc, 0, v0
	v_mov_b32_e32 v1, 0x161
	v_mov_b32_e32 v5, 0x160
	v_cndmask_b32_e32 v1, v5, v1, vcc
	v_mad_u64_u32 v[0:1], s[10:11], v0, v1, v[6:7]
	s_mov_b32 s6, 0x2e8ba2e9
	v_mul_hi_i32 v1, v0, s6
	v_lshrrev_b32_e32 v5, 31, v1
	v_ashrrev_i32_e32 v1, 9, v1
	v_add_u32_e32 v1, v1, v5
	v_mul_i32_i24_e32 v1, 0xb00, v1
	v_sub_u32_e32 v0, v0, v1
	s_movk_i32 s6, 0xba3
	v_mul_i32_i24_sdwa v1, sext(v0), s6 dst_sel:DWORD dst_unused:UNUSED_PAD src0_sel:WORD_0 src1_sel:DWORD
	v_lshrrev_b32_e32 v5, 31, v1
	v_ashrrev_i32_e32 v1, 19, v1
	v_add_u16_e32 v1, v1, v5
	v_mul_lo_u16_e32 v5, 0xb0, v1
	v_sub_u16_e32 v0, v0, v5
	v_ashrrev_i16_e32 v5, 15, v0
	v_lshrrev_b16_e32 v5, 13, v5
	v_add_u16_e32 v5, v0, v5
	v_and_b32_e32 v5, -8, v5
	v_sub_u16_e32 v0, v0, v5
	v_bfe_i32 v1, v1, 0, 16
	v_bfe_i32 v0, v0, 0, 16
	v_lshl_add_u32 v0, v1, 3, v0
	v_ashrrev_i32_e32 v1, 31, v0
	v_lshlrev_b64 v[0:1], 14, v[0:1]
	v_lshl_add_u64 v[0:1], s[28:29], 0, v[0:1]
	v_lshl_add_u64 v[0:1], v[0:1], 0, v[140:141]
	global_load_dwordx4 v[64:67], v[0:1], off
	global_load_dwordx4 v[68:71], v[0:1], off offset:16
	global_load_dwordx4 v[72:75], v[0:1], off offset:32
	global_load_dwordx4 v[76:79], v[0:1], off offset:48
.LBB0_368:
	s_or_b64 exec, exec, s[38:39]
	v_add_u32_e32 v4, 6, v3
	v_mov_b64_e32 v[0:1], s[2:3]
	v_mad_i64_i32 v[0:1], s[10:11], v4, s56, v[0:1]
	s_mov_b64 s[10:11], 0xb00
	s_nop 0
	v_cmp_gt_i64_e32 vcc, s[10:11], v[0:1]
	s_and_saveexec_b64 s[38:39], vcc
	s_cbranch_execz .LBB0_370
	v_ashrrev_i32_e32 v1, 31, v0
	v_lshrrev_b32_e32 v1, 29, v1
	v_add_u32_e32 v1, v0, v1
	v_ashrrev_i32_e32 v6, 3, v1
	v_and_b32_e32 v1, -8, v1
	v_sub_u32_e32 v0, v0, v1
	v_cmp_gt_i32_e32 vcc, 0, v0
	v_mov_b32_e32 v1, 0x161
	v_mov_b32_e32 v5, 0x160
	v_cndmask_b32_e32 v1, v5, v1, vcc
	v_mad_u64_u32 v[0:1], s[10:11], v0, v1, v[6:7]
	s_mov_b32 s6, 0x2e8ba2e9
	v_mul_hi_i32 v1, v0, s6
	v_lshrrev_b32_e32 v5, 31, v1
	v_ashrrev_i32_e32 v1, 9, v1
	v_add_u32_e32 v1, v1, v5
	v_mul_i32_i24_e32 v1, 0xb00, v1
	v_sub_u32_e32 v0, v0, v1
	s_movk_i32 s6, 0xba3
	v_mul_i32_i24_sdwa v1, sext(v0), s6 dst_sel:DWORD dst_unused:UNUSED_PAD src0_sel:WORD_0 src1_sel:DWORD
	v_lshrrev_b32_e32 v5, 31, v1
	v_ashrrev_i32_e32 v1, 19, v1
	v_add_u16_e32 v1, v1, v5
	v_mul_lo_u16_e32 v5, 0xb0, v1
	v_sub_u16_e32 v0, v0, v5
	v_ashrrev_i16_e32 v5, 15, v0
	v_lshrrev_b16_e32 v5, 13, v5
	v_add_u16_e32 v5, v0, v5
	v_and_b32_e32 v5, -8, v5
	v_sub_u16_e32 v0, v0, v5
	v_bfe_i32 v1, v1, 0, 16
	v_bfe_i32 v0, v0, 0, 16
	v_lshl_add_u32 v0, v1, 3, v0
	v_ashrrev_i32_e32 v1, 31, v0
	v_lshlrev_b64 v[0:1], 14, v[0:1]
	v_lshl_add_u64 v[0:1], s[28:29], 0, v[0:1]
	v_lshl_add_u64 v[0:1], v[0:1], 0, v[140:141]
	global_load_dwordx4 v[80:83], v[0:1], off
	global_load_dwordx4 v[84:87], v[0:1], off offset:16
	global_load_dwordx4 v[88:91], v[0:1], off offset:32
	global_load_dwordx4 v[92:95], v[0:1], off offset:48
.LBB0_370:
	s_or_b64 exec, exec, s[38:39]
	v_add_u32_e32 v4, 8, v3
	v_mov_b64_e32 v[0:1], s[2:3]
	v_mad_i64_i32 v[0:1], s[10:11], v4, s56, v[0:1]
	s_mov_b64 s[10:11], 0xb00
	s_nop 0
	v_cmp_gt_i64_e32 vcc, s[10:11], v[0:1]
	s_and_saveexec_b64 s[38:39], vcc
	s_cbranch_execz .LBB0_372
	v_ashrrev_i32_e32 v1, 31, v0
	v_lshrrev_b32_e32 v1, 29, v1
	v_add_u32_e32 v1, v0, v1
	v_ashrrev_i32_e32 v6, 3, v1
	v_and_b32_e32 v1, -8, v1
	v_sub_u32_e32 v0, v0, v1
	v_cmp_gt_i32_e32 vcc, 0, v0
	v_mov_b32_e32 v1, 0x161
	v_mov_b32_e32 v5, 0x160
	v_cndmask_b32_e32 v1, v5, v1, vcc
	v_mad_u64_u32 v[0:1], s[10:11], v0, v1, v[6:7]
	s_mov_b32 s6, 0x2e8ba2e9
	v_mul_hi_i32 v1, v0, s6
	v_lshrrev_b32_e32 v5, 31, v1
	v_ashrrev_i32_e32 v1, 9, v1
	v_add_u32_e32 v1, v1, v5
	v_mul_i32_i24_e32 v1, 0xb00, v1
	v_sub_u32_e32 v0, v0, v1
	s_movk_i32 s6, 0xba3
	v_mul_i32_i24_sdwa v1, sext(v0), s6 dst_sel:DWORD dst_unused:UNUSED_PAD src0_sel:WORD_0 src1_sel:DWORD
	v_lshrrev_b32_e32 v5, 31, v1
	v_ashrrev_i32_e32 v1, 19, v1
	v_add_u16_e32 v1, v1, v5
	v_mul_lo_u16_e32 v5, 0xb0, v1
	v_sub_u16_e32 v0, v0, v5
	v_ashrrev_i16_e32 v5, 15, v0
	v_lshrrev_b16_e32 v5, 13, v5
	v_add_u16_e32 v5, v0, v5
	v_and_b32_e32 v5, -8, v5
	v_sub_u16_e32 v0, v0, v5
	v_bfe_i32 v1, v1, 0, 16
	v_bfe_i32 v0, v0, 0, 16
	v_lshl_add_u32 v0, v1, 3, v0
	v_ashrrev_i32_e32 v1, 31, v0
	v_lshlrev_b64 v[0:1], 14, v[0:1]
	v_lshl_add_u64 v[0:1], s[28:29], 0, v[0:1]
	v_lshl_add_u64 v[0:1], v[0:1], 0, v[140:141]
	global_load_dwordx4 v[96:99], v[0:1], off
	global_load_dwordx4 v[100:103], v[0:1], off offset:16
	global_load_dwordx4 v[104:107], v[0:1], off offset:32
	global_load_dwordx4 v[108:111], v[0:1], off offset:48
.LBB0_372:
	s_or_b64 exec, exec, s[38:39]
	v_add_u32_e32 v4, 10, v3
	v_mov_b64_e32 v[0:1], s[2:3]
	v_mad_i64_i32 v[0:1], s[10:11], v4, s56, v[0:1]
	s_mov_b64 s[10:11], 0xb00
	s_nop 0
	v_cmp_gt_i64_e32 vcc, s[10:11], v[0:1]
	s_and_saveexec_b64 s[38:39], vcc
	s_cbranch_execz .LBB0_374
	v_ashrrev_i32_e32 v1, 31, v0
	v_lshrrev_b32_e32 v1, 29, v1
	v_add_u32_e32 v1, v0, v1
	v_ashrrev_i32_e32 v6, 3, v1
	v_and_b32_e32 v1, -8, v1
	v_sub_u32_e32 v0, v0, v1
	v_cmp_gt_i32_e32 vcc, 0, v0
	v_mov_b32_e32 v1, 0x161
	v_mov_b32_e32 v5, 0x160
	v_cndmask_b32_e32 v1, v5, v1, vcc
	v_mad_u64_u32 v[0:1], s[10:11], v0, v1, v[6:7]
	s_mov_b32 s6, 0x2e8ba2e9
	v_mul_hi_i32 v1, v0, s6
	v_lshrrev_b32_e32 v5, 31, v1
	v_ashrrev_i32_e32 v1, 9, v1
	v_add_u32_e32 v1, v1, v5
	v_mul_i32_i24_e32 v1, 0xb00, v1
	v_sub_u32_e32 v0, v0, v1
	s_movk_i32 s6, 0xba3
	v_mul_i32_i24_sdwa v1, sext(v0), s6 dst_sel:DWORD dst_unused:UNUSED_PAD src0_sel:WORD_0 src1_sel:DWORD
	v_lshrrev_b32_e32 v5, 31, v1
	v_ashrrev_i32_e32 v1, 19, v1
	v_add_u16_e32 v1, v1, v5
	v_mul_lo_u16_e32 v5, 0xb0, v1
	v_sub_u16_e32 v0, v0, v5
	v_ashrrev_i16_e32 v5, 15, v0
	v_lshrrev_b16_e32 v5, 13, v5
	v_add_u16_e32 v5, v0, v5
	v_and_b32_e32 v5, -8, v5
	v_sub_u16_e32 v0, v0, v5
	v_bfe_i32 v1, v1, 0, 16
	v_bfe_i32 v0, v0, 0, 16
	v_lshl_add_u32 v0, v1, 3, v0
	v_ashrrev_i32_e32 v1, 31, v0
	v_lshlrev_b64 v[0:1], 14, v[0:1]
	v_lshl_add_u64 v[0:1], s[28:29], 0, v[0:1]
	v_lshl_add_u64 v[0:1], v[0:1], 0, v[140:141]
	global_load_dwordx4 v[112:115], v[0:1], off
	global_load_dwordx4 v[116:119], v[0:1], off offset:16
	global_load_dwordx4 v[120:123], v[0:1], off offset:32
	global_load_dwordx4 v[124:127], v[0:1], off offset:48
.LBB0_374:
	s_or_b64 exec, exec, s[38:39]
	v_add_u32_e32 v4, 12, v3
	v_mov_b64_e32 v[0:1], s[2:3]
	v_mad_i64_i32 v[0:1], s[10:11], v4, s56, v[0:1]
	s_mov_b64 s[10:11], 0xb00
	s_nop 0
	v_cmp_gt_i64_e32 vcc, s[10:11], v[0:1]
	s_and_saveexec_b64 s[38:39], vcc
	s_cbranch_execz .LBB0_376
	v_ashrrev_i32_e32 v1, 31, v0
	v_lshrrev_b32_e32 v1, 29, v1
	v_add_u32_e32 v1, v0, v1
	v_ashrrev_i32_e32 v6, 3, v1
	v_and_b32_e32 v1, -8, v1
	v_sub_u32_e32 v0, v0, v1
	v_cmp_gt_i32_e32 vcc, 0, v0
	v_mov_b32_e32 v1, 0x161
	v_mov_b32_e32 v5, 0x160
	v_cndmask_b32_e32 v1, v5, v1, vcc
	v_mad_u64_u32 v[0:1], s[10:11], v0, v1, v[6:7]
	s_mov_b32 s6, 0x2e8ba2e9
	v_mul_hi_i32 v1, v0, s6
	v_lshrrev_b32_e32 v5, 31, v1
	v_ashrrev_i32_e32 v1, 9, v1
	v_add_u32_e32 v1, v1, v5
	v_mul_i32_i24_e32 v1, 0xb00, v1
	v_sub_u32_e32 v0, v0, v1
	s_movk_i32 s6, 0xba3
	v_mul_i32_i24_sdwa v1, sext(v0), s6 dst_sel:DWORD dst_unused:UNUSED_PAD src0_sel:WORD_0 src1_sel:DWORD
	v_lshrrev_b32_e32 v5, 31, v1
	v_ashrrev_i32_e32 v1, 19, v1
	v_add_u16_e32 v1, v1, v5
	v_mul_lo_u16_e32 v5, 0xb0, v1
	v_sub_u16_e32 v0, v0, v5
	v_ashrrev_i16_e32 v5, 15, v0
	v_lshrrev_b16_e32 v5, 13, v5
	v_add_u16_e32 v5, v0, v5
	v_and_b32_e32 v5, -8, v5
	v_sub_u16_e32 v0, v0, v5
	v_bfe_i32 v1, v1, 0, 16
	v_bfe_i32 v0, v0, 0, 16
	v_lshl_add_u32 v0, v1, 3, v0
	v_ashrrev_i32_e32 v1, 31, v0
	v_lshlrev_b64 v[0:1], 14, v[0:1]
	v_lshl_add_u64 v[0:1], s[28:29], 0, v[0:1]
	v_lshl_add_u64 v[0:1], v[0:1], 0, v[140:141]
	global_load_dwordx4 v[146:149], v[0:1], off
	global_load_dwordx4 v[150:153], v[0:1], off offset:16
	global_load_dwordx4 v[154:157], v[0:1], off offset:32
	global_load_dwordx4 v[158:161], v[0:1], off offset:48
.LBB0_376:
	s_or_b64 exec, exec, s[38:39]
	v_add_u32_e32 v3, 14, v3
	v_mov_b64_e32 v[0:1], s[2:3]
	v_mad_i64_i32 v[0:1], s[10:11], v3, s56, v[0:1]
	s_mov_b64 s[10:11], 0xb00
	s_nop 0
	v_cmp_gt_i64_e32 vcc, s[10:11], v[0:1]
	s_and_saveexec_b64 s[38:39], vcc
	s_cbranch_execz .LBB0_378
	v_ashrrev_i32_e32 v1, 31, v0
	v_lshrrev_b32_e32 v1, 29, v1
	v_add_u32_e32 v1, v0, v1
	v_ashrrev_i32_e32 v4, 3, v1
	v_and_b32_e32 v1, -8, v1
	v_sub_u32_e32 v0, v0, v1
	v_cmp_gt_i32_e32 vcc, 0, v0
	v_mov_b32_e32 v1, 0x161
	v_mov_b32_e32 v5, 0x160
	v_cndmask_b32_e32 v1, v5, v1, vcc
	v_mad_u64_u32 v[0:1], s[10:11], v0, v1, v[4:5]
	s_mov_b32 s6, 0x2e8ba2e9
	v_mul_hi_i32 v1, v0, s6
	v_lshrrev_b32_e32 v4, 31, v1
	v_ashrrev_i32_e32 v1, 9, v1
	v_add_u32_e32 v1, v1, v4
	v_mul_i32_i24_e32 v1, 0xb00, v1
	v_sub_u32_e32 v0, v0, v1
	s_movk_i32 s6, 0xba3
	v_mul_i32_i24_sdwa v1, sext(v0), s6 dst_sel:DWORD dst_unused:UNUSED_PAD src0_sel:WORD_0 src1_sel:DWORD
	v_lshrrev_b32_e32 v4, 31, v1
	v_ashrrev_i32_e32 v1, 19, v1
	v_add_u16_e32 v1, v1, v4
	v_mul_lo_u16_e32 v4, 0xb0, v1
	v_sub_u16_e32 v0, v0, v4
	v_ashrrev_i16_e32 v4, 15, v0
	v_lshrrev_b16_e32 v4, 13, v4
	v_add_u16_e32 v4, v0, v4
	v_and_b32_e32 v4, -8, v4
	v_sub_u16_e32 v0, v0, v4
	v_bfe_i32 v1, v1, 0, 16
	v_bfe_i32 v0, v0, 0, 16
	v_lshl_add_u32 v0, v1, 3, v0
	v_ashrrev_i32_e32 v1, 31, v0
	v_lshlrev_b64 v[0:1], 14, v[0:1]
	v_lshl_add_u64 v[0:1], s[28:29], 0, v[0:1]
	v_lshl_add_u64 v[0:1], v[0:1], 0, v[140:141]
	global_load_dwordx4 v[162:165], v[0:1], off
	global_load_dwordx4 v[166:169], v[0:1], off offset:16
	global_load_dwordx4 v[170:173], v[0:1], off offset:32
	global_load_dwordx4 v[174:177], v[0:1], off offset:48
.LBB0_378:
	s_or_b64 exec, exec, s[38:39]
	s_waitcnt vmcnt(0)
	v_add_u32_e32 v3, -14, v3
	v_mov_b32_e32 v4, v3
	v_mov_b64_e32 v[0:1], s[2:3]
	v_mad_i64_i32 v[0:1], s[10:11], v4, s56, v[0:1]
	s_mov_b64 s[10:11], 0xb00
	s_nop 0
	v_cmp_gt_i64_e32 vcc, s[10:11], v[0:1]
	s_and_saveexec_b64 s[38:39], vcc
	s_cbranch_execz my_rs2_0
	v_pk_add_f32 v[0:1], v[34:35], v[38:39]
	v_pk_add_f32 v[32:33], v[32:33], v[36:37]
	v_pk_add_f32 v[34:35], v[42:43], v[46:47]
	v_pk_add_f32 v[36:37], v[40:41], v[44:45]
	v_pk_add_f32 v[0:1], v[0:1], v[34:35]
	v_pk_add_f32 v[32:33], v[32:33], v[36:37]
	s_nop 0
	v_pk_mov_b32 v[34:35], v[32:33], v[0:1] op_sel:[1,0]
	v_mov_b32_e32 v33, v1
	v_pk_add_f32 v[0:1], v[34:35], v[32:33]
	s_nop 0
	v_add_f32_e32 v0, v0, v1
	v_fmamk_f32 v0, v0, 0x3a800000, v187
	v_mul_f32_e32 v1, 0x4b800000, v0
	v_cmp_gt_f32_e32 vcc, s78, v0
	s_nop 1
	v_cndmask_b32_e32 v0, v0, v1, vcc
	v_rsq_f32_e32 v0, v0
	s_nop 0
	v_mul_f32_e32 v1, 0x45800000, v0
	v_cndmask_b32_e32 v0, v0, v1, vcc
	v_lshl_add_u32 v1, v3, 10, v2
	ds_write_b32 v1, v0
my_rs2_0:
	s_or_b64 exec, exec, s[38:39]
	v_add_u32_e32 v4, 2, v3
	v_mov_b64_e32 v[0:1], s[2:3]
	v_mad_i64_i32 v[0:1], s[10:11], v4, s56, v[0:1]
	s_mov_b64 s[10:11], 0xb00
	s_nop 0
	v_cmp_gt_i64_e32 vcc, s[10:11], v[0:1]
	s_and_saveexec_b64 s[38:39], vcc
	s_cbranch_execz my_rs2_1
	v_pk_add_f32 v[0:1], v[50:51], v[54:55]
	v_pk_add_f32 v[6:7], v[48:49], v[52:53]
	v_pk_add_f32 v[48:49], v[58:59], v[62:63]
	v_pk_add_f32 v[50:51], v[56:57], v[60:61]
	v_pk_add_f32 v[0:1], v[0:1], v[48:49]
	v_pk_add_f32 v[6:7], v[6:7], v[50:51]
	s_nop 0
	v_pk_mov_b32 v[48:49], v[6:7], v[0:1] op_sel:[1,0]
	v_mov_b32_e32 v7, v1
	v_pk_add_f32 v[0:1], v[48:49], v[6:7]
	s_nop 0
	v_add_f32_e32 v0, v0, v1
	v_fmamk_f32 v0, v0, 0x3a800000, v187
	v_mul_f32_e32 v1, 0x4b800000, v0
	v_cmp_gt_f32_e32 vcc, s78, v0
	s_nop 1
	v_cndmask_b32_e32 v0, v0, v1, vcc
	v_rsq_f32_e32 v0, v0
	s_nop 0
	v_mul_f32_e32 v1, 0x45800000, v0
	v_cndmask_b32_e32 v0, v0, v1, vcc
	v_lshl_add_u32 v1, v4, 10, v2
	ds_write_b32 v1, v0
my_rs2_1:
	s_or_b64 exec, exec, s[38:39]
	v_add_u32_e32 v4, 4, v3
	v_mov_b64_e32 v[0:1], s[2:3]
	v_mad_i64_i32 v[0:1], s[10:11], v4, s56, v[0:1]
	s_mov_b64 s[10:11], 0xb00
	s_nop 0
	v_cmp_gt_i64_e32 vcc, s[10:11], v[0:1]
	s_and_saveexec_b64 s[38:39], vcc
	s_cbranch_execz my_rs2_2
	v_pk_add_f32 v[0:1], v[66:67], v[70:71]
	v_pk_add_f32 v[6:7], v[64:65], v[68:69]
	v_pk_add_f32 v[64:65], v[74:75], v[78:79]
	v_pk_add_f32 v[66:67], v[72:73], v[76:77]
	v_pk_add_f32 v[0:1], v[0:1], v[64:65]
	v_pk_add_f32 v[6:7], v[6:7], v[66:67]
	s_nop 0
	v_pk_mov_b32 v[64:65], v[6:7], v[0:1] op_sel:[1,0]
	v_mov_b32_e32 v7, v1
	v_pk_add_f32 v[0:1], v[64:65], v[6:7]
	s_nop 0
	v_add_f32_e32 v0, v0, v1
	v_fmamk_f32 v0, v0, 0x3a800000, v187
	v_mul_f32_e32 v1, 0x4b800000, v0
	v_cmp_gt_f32_e32 vcc, s78, v0
	s_nop 1
	v_cndmask_b32_e32 v0, v0, v1, vcc
	v_rsq_f32_e32 v0, v0
	s_nop 0
	v_mul_f32_e32 v1, 0x45800000, v0
	v_cndmask_b32_e32 v0, v0, v1, vcc
	v_lshl_add_u32 v1, v4, 10, v2
	ds_write_b32 v1, v0
my_rs2_2:
	s_or_b64 exec, exec, s[38:39]
	v_add_u32_e32 v4, 6, v3
	v_mov_b64_e32 v[0:1], s[2:3]
	v_mad_i64_i32 v[0:1], s[10:11], v4, s56, v[0:1]
	s_mov_b64 s[10:11], 0xb00
	s_nop 0
	v_cmp_gt_i64_e32 vcc, s[10:11], v[0:1]
	s_and_saveexec_b64 s[38:39], vcc
	s_cbranch_execz my_rs2_3
	v_pk_add_f32 v[0:1], v[82:83], v[86:87]
	v_pk_add_f32 v[6:7], v[80:81], v[84:85]
	v_pk_add_f32 v[80:81], v[90:91], v[94:95]
	v_pk_add_f32 v[82:83], v[88:89], v[92:93]
	v_pk_add_f32 v[0:1], v[0:1], v[80:81]
	v_pk_add_f32 v[6:7], v[6:7], v[82:83]
	s_nop 0
	v_pk_mov_b32 v[80:81], v[6:7], v[0:1] op_sel:[1,0]
	v_mov_b32_e32 v7, v1
	v_pk_add_f32 v[0:1], v[80:81], v[6:7]
	s_nop 0
	v_add_f32_e32 v0, v0, v1
	v_fmamk_f32 v0, v0, 0x3a800000, v187
	v_mul_f32_e32 v1, 0x4b800000, v0
	v_cmp_gt_f32_e32 vcc, s78, v0
	s_nop 1
	v_cndmask_b32_e32 v0, v0, v1, vcc
	v_rsq_f32_e32 v0, v0
	s_nop 0
	v_mul_f32_e32 v1, 0x45800000, v0
	v_cndmask_b32_e32 v0, v0, v1, vcc
	v_lshl_add_u32 v1, v4, 10, v2
	ds_write_b32 v1, v0
my_rs2_3:
	s_or_b64 exec, exec, s[38:39]
	v_add_u32_e32 v4, 8, v3
	v_mov_b64_e32 v[0:1], s[2:3]
	v_mad_i64_i32 v[0:1], s[10:11], v4, s56, v[0:1]
	s_mov_b64 s[10:11], 0xb00
	s_nop 0
	v_cmp_gt_i64_e32 vcc, s[10:11], v[0:1]
	s_and_saveexec_b64 s[38:39], vcc
	s_cbranch_execz my_rs2_4
	v_pk_add_f32 v[0:1], v[98:99], v[102:103]
	v_pk_add_f32 v[6:7], v[96:97], v[100:101]
	v_pk_add_f32 v[96:97], v[106:107], v[110:111]
	v_pk_add_f32 v[98:99], v[104:105], v[108:109]
	v_pk_add_f32 v[0:1], v[0:1], v[96:97]
	v_pk_add_f32 v[6:7], v[6:7], v[98:99]
	s_nop 0
	v_pk_mov_b32 v[96:97], v[6:7], v[0:1] op_sel:[1,0]
	v_mov_b32_e32 v7, v1
	v_pk_add_f32 v[0:1], v[96:97], v[6:7]
	s_nop 0
	v_add_f32_e32 v0, v0, v1
	v_fmamk_f32 v0, v0, 0x3a800000, v187
	v_mul_f32_e32 v1, 0x4b800000, v0
	v_cmp_gt_f32_e32 vcc, s78, v0
	s_nop 1
	v_cndmask_b32_e32 v0, v0, v1, vcc
	v_rsq_f32_e32 v0, v0
	s_nop 0
	v_mul_f32_e32 v1, 0x45800000, v0
	v_cndmask_b32_e32 v0, v0, v1, vcc
	v_lshl_add_u32 v1, v4, 10, v2
	ds_write_b32 v1, v0
my_rs2_4:
	s_or_b64 exec, exec, s[38:39]
	v_add_u32_e32 v4, 10, v3
	v_mov_b64_e32 v[0:1], s[2:3]
	v_mad_i64_i32 v[0:1], s[10:11], v4, s56, v[0:1]
	s_mov_b64 s[10:11], 0xb00
	s_nop 0
	v_cmp_gt_i64_e32 vcc, s[10:11], v[0:1]
	s_and_saveexec_b64 s[38:39], vcc
	s_cbranch_execz my_rs2_5
	v_pk_add_f32 v[0:1], v[114:115], v[118:119]
	v_pk_add_f32 v[6:7], v[112:113], v[116:117]
	v_pk_add_f32 v[112:113], v[122:123], v[126:127]
	v_pk_add_f32 v[114:115], v[120:121], v[124:125]
	v_pk_add_f32 v[0:1], v[0:1], v[112:113]
	v_pk_add_f32 v[6:7], v[6:7], v[114:115]
	s_nop 0
	v_pk_mov_b32 v[112:113], v[6:7], v[0:1] op_sel:[1,0]
	v_mov_b32_e32 v7, v1
	v_pk_add_f32 v[0:1], v[112:113], v[6:7]
	s_nop 0
	v_add_f32_e32 v0, v0, v1
	v_fmamk_f32 v0, v0, 0x3a800000, v187
	v_mul_f32_e32 v1, 0x4b800000, v0
	v_cmp_gt_f32_e32 vcc, s78, v0
	s_nop 1
	v_cndmask_b32_e32 v0, v0, v1, vcc
	v_rsq_f32_e32 v0, v0
	s_nop 0
	v_mul_f32_e32 v1, 0x45800000, v0
	v_cndmask_b32_e32 v0, v0, v1, vcc
	v_lshl_add_u32 v1, v4, 10, v2
	ds_write_b32 v1, v0
my_rs2_5:
	s_or_b64 exec, exec, s[38:39]
	v_add_u32_e32 v4, 12, v3
	v_mov_b64_e32 v[0:1], s[2:3]
	v_mad_i64_i32 v[0:1], s[10:11], v4, s56, v[0:1]
	s_mov_b64 s[10:11], 0xb00
	s_nop 0
	v_cmp_gt_i64_e32 vcc, s[10:11], v[0:1]
	s_and_saveexec_b64 s[38:39], vcc
	s_cbranch_execz my_rs2_6
	v_pk_add_f32 v[0:1], v[148:149], v[152:153]
	v_pk_add_f32 v[6:7], v[146:147], v[150:151]
	v_pk_add_f32 v[146:147], v[156:157], v[160:161]
	v_pk_add_f32 v[148:149], v[154:155], v[158:159]
	v_pk_add_f32 v[0:1], v[0:1], v[146:147]
	v_pk_add_f32 v[6:7], v[6:7], v[148:149]
	s_nop 0
	v_pk_mov_b32 v[146:147], v[6:7], v[0:1] op_sel:[1,0]
	v_mov_b32_e32 v7, v1
	v_pk_add_f32 v[0:1], v[146:147], v[6:7]
	s_nop 0
	v_add_f32_e32 v0, v0, v1
	v_fmamk_f32 v0, v0, 0x3a800000, v187
	v_mul_f32_e32 v1, 0x4b800000, v0
	v_cmp_gt_f32_e32 vcc, s78, v0
	s_nop 1
	v_cndmask_b32_e32 v0, v0, v1, vcc
	v_rsq_f32_e32 v0, v0
	s_nop 0
	v_mul_f32_e32 v1, 0x45800000, v0
	v_cndmask_b32_e32 v0, v0, v1, vcc
	v_lshl_add_u32 v1, v4, 10, v2
	ds_write_b32 v1, v0
my_rs2_6:
	s_or_b64 exec, exec, s[38:39]
	v_add_u32_e32 v3, 14, v3
	v_mov_b64_e32 v[0:1], s[2:3]
	v_mad_i64_i32 v[0:1], s[10:11], v3, s56, v[0:1]
	s_mov_b64 s[10:11], 0xb00
	s_nop 0
	v_cmp_gt_i64_e32 vcc, s[10:11], v[0:1]
	s_and_saveexec_b64 s[38:39], vcc
	s_cbranch_execz my_rs2_7
	v_pk_add_f32 v[0:1], v[164:165], v[168:169]
	v_pk_add_f32 v[162:163], v[162:163], v[166:167]
	v_pk_add_f32 v[164:165], v[172:173], v[176:177]
	v_pk_add_f32 v[166:167], v[170:171], v[174:175]
	v_pk_add_f32 v[0:1], v[0:1], v[164:165]
	v_pk_add_f32 v[162:163], v[162:163], v[166:167]
	s_nop 0
	v_pk_mov_b32 v[164:165], v[162:163], v[0:1] op_sel:[1,0]
	v_mov_b32_e32 v163, v1
	v_pk_add_f32 v[0:1], v[164:165], v[162:163]
	s_nop 0
	v_add_f32_e32 v0, v0, v1
	v_fmamk_f32 v0, v0, 0x3a800000, v187
	v_mul_f32_e32 v1, 0x4b800000, v0
	v_cmp_gt_f32_e32 vcc, s78, v0
	s_nop 1
	v_cndmask_b32_e32 v0, v0, v1, vcc
	v_rsq_f32_e32 v0, v0
	s_nop 0
	v_mul_f32_e32 v1, 0x45800000, v0
	v_cndmask_b32_e32 v0, v0, v1, vcc
	v_lshl_add_u32 v1, v3, 10, v2
	ds_write_b32 v1, v0
my_rs2_7:
	s_or_b64 exec, exec, s[38:39]
	v_readlane_b32 s10, v252, 21
	v_readlane_b32 s11, v252, 22
	s_andn2_b64 vcc, exec, s[10:11]
	s_waitcnt vmcnt(0) lgkmcnt(0)
	s_barrier
	s_cbranch_vccnz .LBB0_392
	v_ashrrev_i32_e32 v1, 31, v8
	v_lshrrev_b32_e32 v1, 26, v1
	v_add_u32_e32 v1, v8, v1
	v_ashrrev_i32_e32 v9, 6, v1
	v_bfe_i32 v1, v8, 27, 1
	v_lshlrev_b32_e32 v0, 4, v8
	v_lshrrev_b32_e32 v1, 22, v1
	v_add_u32_e32 v1, v0, v1
	v_and_b32_e32 v1, 0xfffffc00, v1
	v_sub_u32_e32 v1, v0, v1
	v_lshrrev_b32_e32 v2, 4, v1
	v_bitop3_b32 v2, v2, v1, 32 bitop3:0x6c
	v_ashrrev_i32_e32 v1, 31, v1
	v_lshrrev_b32_e32 v1, 26, v1
	v_add_u32_e32 v1, v2, v1
	v_ashrrev_i32_e32 v10, 6, v1
	v_lshlrev_b32_e32 v3, 3, v9
	v_mul_i32_i24_e32 v4, 64, v10
	v_and_b32_e32 v3, -16, v3
	v_sub_u32_e32 v2, v2, v4
	v_mov_b32_e32 v6, 1
	v_add_u32_e32 v1, v10, v3
	v_lshlrev_b32_e32 v3, 5, v9
	v_ashrrev_i16_sdwa v2, v6, sext(v2) dst_sel:DWORD dst_unused:UNUSED_PAD src0_sel:DWORD src1_sel:BYTE_0
	v_and_b32_e32 v3, 32, v3
	v_bfe_i32 v11, v2, 0, 16
	v_and_b32_e32 v5, 3, v10
	s_mov_b32 s10, 0x1fffe0
	v_add_lshl_u32 v3, v3, v11, 1
	v_add_u32_e32 v0, 0x2000, v0
	v_lshlrev_b32_e32 v2, 1, v1
	v_lshrrev_b32_e32 v4, 2, v1
	v_and_or_b32 v5, v1, s10, v5
	v_lshl_add_u32 v128, v1, 11, v3
	v_ashrrev_i32_e32 v1, 31, v0
	v_lshrrev_b32_e32 v1, 22, v1
	v_add_u32_e32 v1, v0, v1
	v_ashrrev_i32_e32 v12, 10, v1
	v_mul_i32_i24_e32 v1, 0x400, v12
	v_sub_u32_e32 v0, v0, v1
	v_and_b32_e32 v2, 24, v2
	v_and_b32_e32 v4, 4, v4
	v_lshrrev_b32_e32 v1, 4, v0
	v_or3_b32 v2, v5, v4, v2
	v_bitop3_b32 v0, v1, v0, 32 bitop3:0x6c
	v_lshl_add_u32 v140, v2, 11, v3
	v_ashrrev_i32_e32 v2, 31, v0
	v_lshrrev_b32_e32 v2, 26, v2
	v_lshlrev_b32_e32 v1, 3, v12
	v_add_u32_e32 v2, v0, v2
	v_and_b32_e32 v1, -16, v1
	v_ashrrev_i32_e32 v13, 6, v2
	s_add_u32 s33, s34, 0x12290000
	v_add_u32_e32 v1, v13, v1
	v_and_b32_e32 v4, 3, v13
	s_addc_u32 s41, s35, 0
	v_and_b32_e32 v2, 0xc0, v2
	v_and_or_b32 v4, v1, s10, v4
	s_ashr_i32 s10, s9, 6
	s_ashr_i32 s6, s9, 8
	v_sub_u32_e32 v0, v0, v2
	s_lshl_b32 s57, s10, 10
	v_readlane_b32 s28, v253, 50
	v_ashrrev_i16_sdwa v0, v6, sext(v0) dst_sel:DWORD dst_unused:UNUSED_PAD src0_sel:DWORD src1_sel:BYTE_0
	v_readlane_b32 s29, v253, 51
	s_add_u32 s52, s26, s28
	v_lshlrev_b32_e32 v3, 5, v12
	v_bfe_i32 v14, v0, 0, 16
	v_lshlrev_b32_e32 v0, 1, v1
	v_lshrrev_b32_e32 v2, 2, v1
	s_addc_u32 s53, s27, s29
	s_add_i32 s68, s57, 0
	v_and_b32_e32 v3, 32, v3
	v_and_b32_e32 v0, 24, v0
	v_and_b32_e32 v2, 4, v2
	s_add_i32 m0, s68, 0x10000
	v_or3_b32 v0, v4, v2, v0
	v_add_lshl_u32 v2, v3, v14, 1
	global_load_lds_dwordx4 v140, s[52:53]
	s_add_i32 m0, s68, 0x12000
	v_readlane_b32 s28, v254, 2
	v_lshl_add_u32 v132, v0, 11, v2
	v_readlane_b32 s29, v254, 3
	s_add_u32 s28, s33, s28
	global_load_lds_dwordx4 v132, s[52:53]
	s_addc_u32 s29, s41, s29
	s_mov_b32 m0, s68
	s_add_i32 s69, s68, 0x2000
	v_lshl_add_u32 v130, v1, 11, v2
	global_load_lds_dwordx4 v128, s[28:29]
	s_mov_b32 m0, s69
	s_add_u32 s34, s52, 0x40000
	global_load_lds_dwordx4 v130, s[28:29]
	s_addc_u32 s35, s53, 0
	s_add_i32 m0, s68, 0x14000
	v_mov_b32_e32 v133, v141
	global_load_lds_dwordx4 v140, s[34:35]
	s_add_i32 m0, s68, 0x16000
	v_mov_b32_e32 v129, v141
	global_load_lds_dwordx4 v132, s[34:35]
	s_add_u32 s34, s28, 0x40000
	s_addc_u32 s35, s29, 0
	s_add_i32 s70, s68, 0x4000
	s_mov_b32 m0, s70
	s_add_i32 s71, s68, 0x6000
	global_load_lds_dwordx4 v128, s[34:35]
	s_mov_b32 m0, s71
	v_mov_b32_e32 v131, v141
	global_load_lds_dwordx4 v130, s[34:35]
	v_lshl_add_u64 v[6:7], s[52:53], 0, v[140:141]
	v_lshl_add_u64 v[4:5], s[52:53], 0, v[132:133]
	v_lshl_add_u64 v[2:3], s[28:29], 0, v[128:129]
	s_cmp_lg_u32 s6, 1
	v_lshl_add_u64 v[0:1], s[28:29], 0, v[130:131]
	s_cbranch_scc1 .LBB0_381
	s_barrier
